# GEMM K-loops: the M0-write to LDS-DMA wait states are filled with the segment's own A-fragment ds_reads instead of s_nop 0
# speedup vs baseline: 1.0093x; 1.0007x over previous
; #define PG8_STAGE(bufoff, gbase, voff) do { _Pragma("unroll") for (int _i = 0; _i < 2; ++_i) \
;         __builtin_amdgcn_global_load_lds((const unsigned*)((const char*)(gbase) + (voff)[_i]), (LAS unsigned*)(lds + (bufoff) + ldsw + _i * 8192), 16, 0, 0); } while (0)
; #define PG8_LDA(dst, b, h) do { _Pragma("unroll") for (int m = 0; m < 4; ++m) _Pragma("unroll") for (int k = 0; k < 2; ++k) dst[m][k] = *(const LAS bf16x8*)(lds + PG8_SA(b, h) + aoff + m * 2048 + k * 1024); } while (0)
; #define PG8_LDB(dst, b, h) do { _Pragma("unroll") for (int n = 0; n < 2; ++n) _Pragma("unroll") for (int k = 0; k < 2; ++k) dst[n][k] = *(const LAS bf16x8*)(lds + PG8_SB(b, h) + boff + n * 2048 + k * 1024); } while (0)
; #define PG8_MMA(ai, bj, At, Bt) do { __builtin_amdgcn_s_setprio(1); _Pragma("unroll") for (int m = 0; m < 4; ++m) _Pragma("unroll") for (int n = 0; n < 2; ++n) _Pragma("unroll") for (int k = 0; k < 2; ++k) \
;         acc[ai][bj][m][n] = __builtin_amdgcn_mfma_f32_16x16x32_bf16(Bt[n][k], At[m][k], acc[ai][bj][m][n], 0, 0, 0); __builtin_amdgcn_s_setprio(0); } while (0)
; #define PG8_WAIT_V(n) asm volatile("s_waitcnt vmcnt(" #n ")" ::: "memory")
; #define PG8_WAIT_L(n) asm volatile("s_waitcnt lgkmcnt(" #n ")" ::: "memory")
; #define PG8_BAR __builtin_amdgcn_s_barrier()
; template <class Epi, class Sched>
; DI void gemm_phase(LAS unsigned char* lds, const Sched& S, const Epi& E) {
;     ...
;         for (int t = 0; t < nt; t += 2) {
;             const bool last = (t == nt - 2);
;             const char* a1 = cA + (size_t)(t + 1) * kstep;
;             const char* a2 = last ? nA : cA + (size_t)(t + 2) * kstep; const char* b2 = last ? nB : cB + (size_t)(t + 2) * kstep;
;             const char* a3 = a2 + kstep; const char* b3 = b2 + kstep;
;             if constexpr (Epi::HOOK) { if (cur.ks < 0 && (t == 16 || t == 32)) E.hook(acc, cur, t >> 4, wr, wc, fr, fq); }
;             PG8_LDB(B0, 0, 0); PG8_LDB(B1, 0, 1); PG8_SCHED; PG8_LDA(At, 0, 0); PG8_STAGE(PG8_SA(1, 1), a1 + hstepA, voffA);
;             PG8_WAIT_V(8); PG8_WAIT_L(0); PG8_BAR; PG8_MMA(0, 0, At, B0); PG8_MMA(0, 1, At, B1); PG8_BAR; PG8_SCHED;
;             PG8_LDA(At, 0, 1); PG8_STAGE(PG8_SB(0, 0), b2, voffB); PG8_STAGE(PG8_SB(0, 1), b2 + hstepB, voffB); PG8_STAGE(PG8_SA(0, 0), a2, voffA);
;             PG8_WAIT_V(8); PG8_WAIT_L(0); PG8_BAR; PG8_MMA(1, 0, At, B0); PG8_MMA(1, 1, At, B1); PG8_BAR; PG8_SCHED;
.LBB0_156:
	s_add_i32 s82, s8, 2
	s_add_u32 s9, s4, 0xfff80080
	s_addc_u32 s40, s5, -1
	s_add_i32 s83, 0, 0x10000
	s_cmp_eq_u32 s79, s8
	s_cselect_b32 s41, s42, s40
	s_cselect_b32 s40, s43, s9
	v_add_u32_e32 v2, s83, v145
	s_cselect_b32 s9, s53, s81
	s_cselect_b32 s8, s57, s80
	s_add_i32 s85, 0, 0x14000
	ds_read_b128 v[52:55], v2
	ds_read_b128 v[156:159], v2 offset:1024
	ds_read_b128 v[160:163], v2 offset:2048
	ds_read_b128 v[168:171], v2 offset:3072
	v_add_u32_e32 v2, s85, v145
	ds_read_b128 v[172:175], v2
	ds_read_b128 v[176:179], v2 offset:1024
	ds_read_b128 v[180:183], v2 offset:2048
	ds_read_b128 v[184:187], v2 offset:3072
	s_add_i32 m0, s62, 0xc000
	ds_read_b128 v[188:191], v166
	ds_read_b128 v[192:195], v166 offset:1024
	ds_read_b128 v[204:207], v166 offset:2048
	ds_read_b128 v[208:211], v166 offset:3072
	ds_read_b128 v[212:215], v166 offset:4096
	ds_read_b128 v[230:233], v166 offset:5120
	ds_read_b128 v[234:237], v166 offset:6144
	global_load_lds_dwordx4 v154, s[4:5]
	s_add_i32 m0, s62, 0xe000
	ds_read_b128 v[238:241], v166 offset:7168
	global_load_lds_dwordx4 v152, s[4:5]
	s_waitcnt vmcnt(8)
	s_waitcnt lgkmcnt(0)
	s_barrier
	s_setprio 1
	s_waitcnt lgkmcnt(0)
	v_mfma_f32_16x16x32_bf16 v[132:135], v[52:55], v[188:191], v[132:135]
	v_mfma_f32_16x16x32_bf16 v[128:131], v[160:163], v[188:191], v[128:131]
	v_mfma_f32_16x16x32_bf16 v[116:119], v[52:55], v[204:207], v[116:119]
	v_mfma_f32_16x16x32_bf16 v[112:115], v[160:163], v[204:207], v[112:115]
	v_mfma_f32_16x16x32_bf16 v[100:103], v[52:55], v[212:215], v[100:103]
	v_mfma_f32_16x16x32_bf16 v[96:99], v[160:163], v[212:215], v[96:99]
	v_mfma_f32_16x16x32_bf16 v[84:87], v[52:55], v[234:237], v[84:87]
	v_mfma_f32_16x16x32_bf16 v[80:83], v[160:163], v[234:237], v[80:83]
	v_mfma_f32_16x16x32_bf16 v[132:135], v[156:159], v[192:195], v[132:135]
	v_mfma_f32_16x16x32_bf16 v[128:131], v[168:171], v[192:195], v[128:131]
	v_mfma_f32_16x16x32_bf16 v[116:119], v[156:159], v[208:211], v[116:119]
	v_mfma_f32_16x16x32_bf16 v[112:115], v[168:171], v[208:211], v[112:115]
	v_mfma_f32_16x16x32_bf16 v[100:103], v[156:159], v[230:233], v[100:103]
	v_mfma_f32_16x16x32_bf16 v[96:99], v[168:171], v[230:233], v[96:99]
	v_mfma_f32_16x16x32_bf16 v[84:87], v[156:159], v[238:241], v[84:87]
	v_mfma_f32_16x16x32_bf16 v[80:83], v[168:171], v[238:241], v[80:83]
	s_setprio 0
	s_setprio 1
	v_mfma_f32_16x16x32_bf16 v[124:127], v[172:175], v[188:191], v[124:127]
	v_mfma_f32_16x16x32_bf16 v[120:123], v[180:183], v[188:191], v[120:123]
	v_mfma_f32_16x16x32_bf16 v[108:111], v[172:175], v[204:207], v[108:111]
	v_mfma_f32_16x16x32_bf16 v[104:107], v[180:183], v[204:207], v[104:107]
	v_mfma_f32_16x16x32_bf16 v[92:95], v[172:175], v[212:215], v[92:95]
	v_mfma_f32_16x16x32_bf16 v[88:91], v[180:183], v[212:215], v[88:91]
	v_mfma_f32_16x16x32_bf16 v[76:79], v[172:175], v[234:237], v[76:79]
	v_mfma_f32_16x16x32_bf16 v[72:75], v[180:183], v[234:237], v[72:75]
	v_mfma_f32_16x16x32_bf16 v[124:127], v[176:179], v[192:195], v[124:127]
	v_mfma_f32_16x16x32_bf16 v[120:123], v[184:187], v[192:195], v[120:123]
	v_mfma_f32_16x16x32_bf16 v[108:111], v[176:179], v[208:211], v[108:111]
	v_mfma_f32_16x16x32_bf16 v[104:107], v[184:187], v[208:211], v[104:107]
	v_mfma_f32_16x16x32_bf16 v[92:95], v[176:179], v[230:233], v[92:95]
	v_mfma_f32_16x16x32_bf16 v[88:91], v[184:187], v[230:233], v[88:91]
	v_mfma_f32_16x16x32_bf16 v[76:79], v[176:179], v[238:241], v[76:79]
	v_mfma_f32_16x16x32_bf16 v[72:75], v[184:187], v[238:241], v[72:75]
	s_setprio 0
	s_barrier
	s_add_i32 s83, s83, s27
	s_mov_b32 m0, s83
	ds_read_b128 v[188:191], v166 offset:16384
	ds_read_b128 v[192:195], v166 offset:17408
	ds_read_b128 v[204:207], v166 offset:18432
	ds_read_b128 v[208:211], v166 offset:19456
	global_load_lds_dwordx4 v138, s[8:9]
	s_add_i32 m0, s83, 0x2000
	s_add_u32 s86, s8, 0x80000
	s_addc_u32 s87, s9, 0
	s_add_i32 s83, s85, s27
	global_load_lds_dwordx4 v142, s[8:9]
	s_mov_b32 m0, s83
	ds_read_b128 v[238:241], v166 offset:23552
	global_load_lds_dwordx4 v138, s[86:87]
	s_add_i32 m0, s83, 0x2000
	ds_read_b128 v[234:237], v166 offset:22528
	global_load_lds_dwordx4 v142, s[86:87]
	s_add_u32 s98, s40, 0x80
	s_addc_u32 s99, s41, 0
	s_mov_b32 m0, s62
	ds_read_b128 v[230:233], v166 offset:21504
	global_load_lds_dwordx4 v136, s[40:41]
	s_mov_b32 m0, s63
	ds_read_b128 v[212:215], v166 offset:20480
	global_load_lds_dwordx4 v140, s[40:41]
	s_waitcnt vmcnt(8)
	s_waitcnt lgkmcnt(0)
	s_barrier
	s_setprio 1
	s_waitcnt lgkmcnt(0)
	v_mfma_f32_16x16x32_bf16 v[68:71], v[52:55], v[188:191], v[68:71]
	v_mfma_f32_16x16x32_bf16 v[64:67], v[160:163], v[188:191], v[64:67]
	v_mfma_f32_16x16x32_bf16 v[48:51], v[52:55], v[204:207], v[48:51]
	v_mfma_f32_16x16x32_bf16 v[44:47], v[160:163], v[204:207], v[44:47]
	v_mfma_f32_16x16x32_bf16 v[32:35], v[52:55], v[212:215], v[32:35]
	v_mfma_f32_16x16x32_bf16 v[28:31], v[160:163], v[212:215], v[28:31]
	v_mfma_f32_16x16x32_bf16 v[16:19], v[52:55], v[234:237], v[16:19]
	v_mfma_f32_16x16x32_bf16 v[12:15], v[160:163], v[234:237], v[12:15]
	v_mfma_f32_16x16x32_bf16 v[68:71], v[156:159], v[192:195], v[68:71]
	v_mfma_f32_16x16x32_bf16 v[64:67], v[168:171], v[192:195], v[64:67]
	v_mfma_f32_16x16x32_bf16 v[48:51], v[156:159], v[208:211], v[48:51]
	v_mfma_f32_16x16x32_bf16 v[44:47], v[168:171], v[208:211], v[44:47]
	v_mfma_f32_16x16x32_bf16 v[32:35], v[156:159], v[230:233], v[32:35]
	v_mfma_f32_16x16x32_bf16 v[28:31], v[168:171], v[230:233], v[28:31]
	v_mfma_f32_16x16x32_bf16 v[16:19], v[156:159], v[238:241], v[16:19]
	v_mfma_f32_16x16x32_bf16 v[12:15], v[168:171], v[238:241], v[12:15]
	s_setprio 0
	s_setprio 1
	v_mfma_f32_16x16x32_bf16 v[56:59], v[180:183], v[188:191], v[56:59]
	v_mfma_f32_16x16x32_bf16 v[40:43], v[172:175], v[204:207], v[40:43]
	v_mfma_f32_16x16x32_bf16 v[36:39], v[180:183], v[204:207], v[36:39]
	v_mfma_f32_16x16x32_bf16 v[24:27], v[172:175], v[212:215], v[24:27]
	v_mfma_f32_16x16x32_bf16 v[20:23], v[180:183], v[212:215], v[20:23]
	v_mfma_f32_16x16x32_bf16 v[8:11], v[172:175], v[234:237], v[8:11]
	v_mfma_f32_16x16x32_bf16 v[4:7], v[180:183], v[234:237], v[4:7]
	v_mfma_f32_16x16x32_bf16 v[52:55], v[172:175], v[188:191], v[60:63]
	v_mfma_f32_16x16x32_bf16 v[56:59], v[184:187], v[192:195], v[56:59]
	v_mfma_f32_16x16x32_bf16 v[40:43], v[176:179], v[208:211], v[40:43]
	v_mfma_f32_16x16x32_bf16 v[36:39], v[184:187], v[208:211], v[36:39]
	v_mfma_f32_16x16x32_bf16 v[24:27], v[176:179], v[230:233], v[24:27]
	v_mfma_f32_16x16x32_bf16 v[20:23], v[184:187], v[230:233], v[20:23]
	v_mfma_f32_16x16x32_bf16 v[8:11], v[176:179], v[238:241], v[8:11]
	v_mfma_f32_16x16x32_bf16 v[4:7], v[184:187], v[238:241], v[4:7]
	v_mfma_f32_16x16x32_bf16 v[52:55], v[176:179], v[192:195], v[52:55]
	s_setprio 0
	s_barrier
; #define PG8_STAGE(bufoff, gbase, voff) do { _Pragma("unroll") for (int _i = 0; _i < 2; ++_i) \
;         __builtin_amdgcn_global_load_lds((const unsigned*)((const char*)(gbase) + (voff)[_i]), (LAS unsigned*)(lds + (bufoff) + ldsw + _i * 8192), 16, 0, 0); } while (0)
; #define PG8_LDA(dst, b, h) do { _Pragma("unroll") for (int m = 0; m < 4; ++m) _Pragma("unroll") for (int k = 0; k < 2; ++k) dst[m][k] = *(const LAS bf16x8*)(lds + PG8_SA(b, h) + aoff + m * 2048 + k * 1024); } while (0)
; #define PG8_LDB(dst, b, h) do { _Pragma("unroll") for (int n = 0; n < 2; ++n) _Pragma("unroll") for (int k = 0; k < 2; ++k) dst[n][k] = *(const LAS bf16x8*)(lds + PG8_SB(b, h) + boff + n * 2048 + k * 1024); } while (0)
; #define PG8_MMA(ai, bj, At, Bt) do { __builtin_amdgcn_s_setprio(1); _Pragma("unroll") for (int m = 0; m < 4; ++m) _Pragma("unroll") for (int n = 0; n < 2; ++n) _Pragma("unroll") for (int k = 0; k < 2; ++k) \
;         acc[ai][bj][m][n] = __builtin_amdgcn_mfma_f32_16x16x32_bf16(Bt[n][k], At[m][k], acc[ai][bj][m][n], 0, 0, 0); __builtin_amdgcn_s_setprio(0); } while (0)
; #define PG8_WAIT_V(n) asm volatile("s_waitcnt vmcnt(" #n ")" ::: "memory")
; #define PG8_WAIT_L(n) asm volatile("s_waitcnt lgkmcnt(" #n ")" ::: "memory")
; #define PG8_BAR __builtin_amdgcn_s_barrier()
; #define PG8_SCHED __builtin_amdgcn_sched_barrier(0)
; template <class Epi, class Sched>
; DI void gemm_phase(LAS unsigned char* lds, const Sched& S, const Epi& E) {
;     ...
;             PG8_LDB(B0, 1, 0); PG8_LDB(B1, 1, 1); PG8_SCHED; PG8_LDA(At, 1, 0); PG8_STAGE(PG8_SA(0, 1), a2 + hstepA, voffA);
;             PG8_WAIT_V(8); PG8_WAIT_L(0); PG8_BAR; PG8_MMA(0, 0, At, B0); PG8_MMA(0, 1, At, B1); PG8_BAR; PG8_SCHED;
;             PG8_LDA(At, 1, 1); PG8_STAGE(PG8_SB(1, 0), b3, voffB); PG8_STAGE(PG8_SB(1, 1), b3 + hstepB, voffB); PG8_STAGE(PG8_SA(1, 0), a3, voffA);
;             PG8_WAIT_V(8); PG8_WAIT_L(0); PG8_BAR; PG8_MMA(1, 0, At, B0); PG8_MMA(1, 1, At, B1); PG8_BAR; PG8_SCHED;
;         }
	s_add_i32 s83, 0, 0x18000
	v_add_u32_e32 v2, s83, v145
	s_add_i32 s85, 0, 0x1c000
	ds_read_b128 v[60:63], v2
	ds_read_b128 v[156:159], v2 offset:1024
	ds_read_b128 v[160:163], v2 offset:2048
	ds_read_b128 v[168:171], v2 offset:3072
	v_add_u32_e32 v2, s85, v145
	ds_read_b128 v[172:175], v2
	ds_read_b128 v[176:179], v2 offset:1024
	ds_read_b128 v[180:183], v2 offset:2048
	ds_read_b128 v[184:187], v2 offset:3072
	s_add_u32 s40, s40, 0x80000
	s_addc_u32 s41, s41, 0
	s_mov_b32 m0, s64
	ds_read_b128 v[188:191], v166 offset:32768
	ds_read_b128 v[192:195], v166 offset:33792
	ds_read_b128 v[204:207], v166 offset:34816
	ds_read_b128 v[208:211], v166 offset:35840
	ds_read_b128 v[212:215], v166 offset:36864
	ds_read_b128 v[230:233], v166 offset:37888
	ds_read_b128 v[234:237], v166 offset:38912
	global_load_lds_dwordx4 v136, s[40:41]
	s_mov_b32 m0, s65
	ds_read_b128 v[238:241], v166 offset:39936
	global_load_lds_dwordx4 v140, s[40:41]
	s_waitcnt vmcnt(8)
	s_waitcnt lgkmcnt(0)
	s_barrier
	s_setprio 1
	s_waitcnt lgkmcnt(0)
	v_mfma_f32_16x16x32_bf16 v[132:135], v[60:63], v[188:191], v[132:135]
	v_mfma_f32_16x16x32_bf16 v[128:131], v[160:163], v[188:191], v[128:131]
	v_mfma_f32_16x16x32_bf16 v[116:119], v[60:63], v[204:207], v[116:119]
	v_mfma_f32_16x16x32_bf16 v[112:115], v[160:163], v[204:207], v[112:115]
	v_mfma_f32_16x16x32_bf16 v[100:103], v[60:63], v[212:215], v[100:103]
	v_mfma_f32_16x16x32_bf16 v[96:99], v[160:163], v[212:215], v[96:99]
	v_mfma_f32_16x16x32_bf16 v[84:87], v[60:63], v[234:237], v[84:87]
	v_mfma_f32_16x16x32_bf16 v[80:83], v[160:163], v[234:237], v[80:83]
	v_mfma_f32_16x16x32_bf16 v[132:135], v[156:159], v[192:195], v[132:135]
	v_mfma_f32_16x16x32_bf16 v[128:131], v[168:171], v[192:195], v[128:131]
	v_mfma_f32_16x16x32_bf16 v[116:119], v[156:159], v[208:211], v[116:119]
	v_mfma_f32_16x16x32_bf16 v[112:115], v[168:171], v[208:211], v[112:115]
	v_mfma_f32_16x16x32_bf16 v[100:103], v[156:159], v[230:233], v[100:103]
	v_mfma_f32_16x16x32_bf16 v[96:99], v[168:171], v[230:233], v[96:99]
	v_mfma_f32_16x16x32_bf16 v[84:87], v[156:159], v[238:241], v[84:87]
	v_mfma_f32_16x16x32_bf16 v[80:83], v[168:171], v[238:241], v[80:83]
	s_setprio 0
	s_setprio 1
	v_mfma_f32_16x16x32_bf16 v[124:127], v[172:175], v[188:191], v[124:127]
	v_mfma_f32_16x16x32_bf16 v[120:123], v[180:183], v[188:191], v[120:123]
	v_mfma_f32_16x16x32_bf16 v[108:111], v[172:175], v[204:207], v[108:111]
	v_mfma_f32_16x16x32_bf16 v[104:107], v[180:183], v[204:207], v[104:107]
	v_mfma_f32_16x16x32_bf16 v[92:95], v[172:175], v[212:215], v[92:95]
	v_mfma_f32_16x16x32_bf16 v[88:91], v[180:183], v[212:215], v[88:91]
	v_mfma_f32_16x16x32_bf16 v[76:79], v[172:175], v[234:237], v[76:79]
	v_mfma_f32_16x16x32_bf16 v[72:75], v[180:183], v[234:237], v[72:75]
	v_mfma_f32_16x16x32_bf16 v[124:127], v[176:179], v[192:195], v[124:127]
	v_mfma_f32_16x16x32_bf16 v[120:123], v[184:187], v[192:195], v[120:123]
	v_mfma_f32_16x16x32_bf16 v[108:111], v[176:179], v[208:211], v[108:111]
	v_mfma_f32_16x16x32_bf16 v[104:107], v[184:187], v[208:211], v[104:107]
	v_mfma_f32_16x16x32_bf16 v[92:95], v[176:179], v[230:233], v[92:95]
	v_mfma_f32_16x16x32_bf16 v[88:91], v[184:187], v[230:233], v[88:91]
	v_mfma_f32_16x16x32_bf16 v[76:79], v[176:179], v[238:241], v[76:79]
	v_mfma_f32_16x16x32_bf16 v[72:75], v[184:187], v[238:241], v[72:75]
	s_setprio 0
	s_barrier
	s_add_i32 s40, s83, s27
	s_add_u32 s8, s8, 0x80
	s_addc_u32 s9, s9, 0
	s_mov_b32 m0, s40
	ds_read_b128 v[188:191], v166 offset:49152
	ds_read_b128 v[192:195], v166 offset:50176
	ds_read_b128 v[204:207], v166 offset:51200
	ds_read_b128 v[208:211], v166 offset:52224
	global_load_lds_dwordx4 v138, s[8:9]
	s_add_i32 m0, s40, 0x2000
	s_add_i32 s40, s85, s27
	global_load_lds_dwordx4 v142, s[8:9]
	s_add_u32 s8, s8, 0x80000
	s_addc_u32 s9, s9, 0
	s_mov_b32 m0, s40
	ds_read_b128 v[238:241], v166 offset:56320
	global_load_lds_dwordx4 v138, s[8:9]
	s_add_i32 m0, s40, 0x2000
	ds_read_b128 v[234:237], v166 offset:55296
	global_load_lds_dwordx4 v142, s[8:9]
	s_mov_b32 m0, s72
	ds_read_b128 v[230:233], v166 offset:54272
	global_load_lds_dwordx4 v136, s[98:99]
	s_mov_b32 m0, s73
	ds_read_b128 v[212:215], v166 offset:53248
	global_load_lds_dwordx4 v140, s[98:99]
	s_waitcnt vmcnt(8)
	s_waitcnt lgkmcnt(0)
	s_barrier
	s_setprio 1
	s_waitcnt lgkmcnt(0)
	v_mfma_f32_16x16x32_bf16 v[68:71], v[60:63], v[188:191], v[68:71]
	v_mfma_f32_16x16x32_bf16 v[64:67], v[160:163], v[188:191], v[64:67]
	v_mfma_f32_16x16x32_bf16 v[48:51], v[60:63], v[204:207], v[48:51]
	v_mfma_f32_16x16x32_bf16 v[44:47], v[160:163], v[204:207], v[44:47]
	v_mfma_f32_16x16x32_bf16 v[32:35], v[60:63], v[212:215], v[32:35]
	v_mfma_f32_16x16x32_bf16 v[28:31], v[160:163], v[212:215], v[28:31]
	v_mfma_f32_16x16x32_bf16 v[16:19], v[60:63], v[234:237], v[16:19]
	v_mfma_f32_16x16x32_bf16 v[12:15], v[160:163], v[234:237], v[12:15]
	v_mfma_f32_16x16x32_bf16 v[68:71], v[156:159], v[192:195], v[68:71]
	v_mfma_f32_16x16x32_bf16 v[64:67], v[168:171], v[192:195], v[64:67]
	v_mfma_f32_16x16x32_bf16 v[48:51], v[156:159], v[208:211], v[48:51]
	v_mfma_f32_16x16x32_bf16 v[44:47], v[168:171], v[208:211], v[44:47]
	v_mfma_f32_16x16x32_bf16 v[32:35], v[156:159], v[230:233], v[32:35]
	v_mfma_f32_16x16x32_bf16 v[28:31], v[168:171], v[230:233], v[28:31]
	v_mfma_f32_16x16x32_bf16 v[16:19], v[156:159], v[238:241], v[16:19]
	v_mfma_f32_16x16x32_bf16 v[12:15], v[168:171], v[238:241], v[12:15]
	s_setprio 0
	s_setprio 1
	v_mfma_f32_16x16x32_bf16 v[52:55], v[172:175], v[188:191], v[52:55]
	v_mfma_f32_16x16x32_bf16 v[60:63], v[176:179], v[192:195], v[52:55]
	v_mfma_f32_16x16x32_bf16 v[52:55], v[180:183], v[188:191], v[56:59]
	v_mfma_f32_16x16x32_bf16 v[40:43], v[172:175], v[204:207], v[40:43]
	v_mfma_f32_16x16x32_bf16 v[36:39], v[180:183], v[204:207], v[36:39]
	v_mfma_f32_16x16x32_bf16 v[24:27], v[172:175], v[212:215], v[24:27]
	v_mfma_f32_16x16x32_bf16 v[20:23], v[180:183], v[212:215], v[20:23]
	v_mfma_f32_16x16x32_bf16 v[8:11], v[172:175], v[234:237], v[8:11]
	v_mfma_f32_16x16x32_bf16 v[4:7], v[180:183], v[234:237], v[4:7]
	v_mfma_f32_16x16x32_bf16 v[56:59], v[184:187], v[192:195], v[52:55]
	v_mfma_f32_16x16x32_bf16 v[40:43], v[176:179], v[208:211], v[40:43]
	v_mfma_f32_16x16x32_bf16 v[36:39], v[184:187], v[208:211], v[36:39]
	v_mfma_f32_16x16x32_bf16 v[24:27], v[176:179], v[230:233], v[24:27]
	v_mfma_f32_16x16x32_bf16 v[20:23], v[184:187], v[230:233], v[20:23]
	v_mfma_f32_16x16x32_bf16 v[8:11], v[176:179], v[238:241], v[8:11]
	v_mfma_f32_16x16x32_bf16 v[4:7], v[184:187], v[238:241], v[4:7]
	s_setprio 0
	s_barrier
	s_add_u32 s80, s80, 0x100
	s_addc_u32 s81, s81, 0
	s_add_u32 s4, s4, 0x100
	s_addc_u32 s5, s5, 0
	s_cmp_ge_i32 s82, s35
	s_mov_b32 s8, s82
	s_cbranch_scc0 .LBB0_156
	s_and_b64 vcc, exec, s[48:49]
	s_cbranch_vccz .LBB0_159
	s_barrier

; #define PG8_STAGE(bufoff, gbase, voff) do { _Pragma("unroll") for (int _i = 0; _i < 2; ++_i) \
;         __builtin_amdgcn_global_load_lds((const unsigned*)((const char*)(gbase) + (voff)[_i]), (LAS unsigned*)(lds + (bufoff) + ldsw + _i * 8192), 16, 0, 0); } while (0)
; #define PG8_LDA(dst, b, h) do { _Pragma("unroll") for (int m = 0; m < 4; ++m) _Pragma("unroll") for (int k = 0; k < 2; ++k) dst[m][k] = *(const LAS bf16x8*)(lds + PG8_SA(b, h) + aoff + m * 2048 + k * 1024); } while (0)
; #define PG8_LDB(dst, b, h) do { _Pragma("unroll") for (int n = 0; n < 2; ++n) _Pragma("unroll") for (int k = 0; k < 2; ++k) dst[n][k] = *(const LAS bf16x8*)(lds + PG8_SB(b, h) + boff + n * 2048 + k * 1024); } while (0)
; #define PG8_MMA(ai, bj, At, Bt) do { __builtin_amdgcn_s_setprio(1); _Pragma("unroll") for (int m = 0; m < 4; ++m) _Pragma("unroll") for (int n = 0; n < 2; ++n) _Pragma("unroll") for (int k = 0; k < 2; ++k) \
;         acc[ai][bj][m][n] = __builtin_amdgcn_mfma_f32_16x16x32_bf16(Bt[n][k], At[m][k], acc[ai][bj][m][n], 0, 0, 0); __builtin_amdgcn_s_setprio(0); } while (0)
; #define PG8_WAIT_V(n) asm volatile("s_waitcnt vmcnt(" #n ")" ::: "memory")
; #define PG8_WAIT_L(n) asm volatile("s_waitcnt lgkmcnt(" #n ")" ::: "memory")
; #define PG8_BAR __builtin_amdgcn_s_barrier()
; template <class Epi, class Sched>
; DI void gemm_phase(LAS unsigned char* lds, const Sched& S, const Epi& E) {
;     ...
;         for (int t = 0; t < nt; t += 2) {
;             const bool last = (t == nt - 2);
;             const char* a1 = cA + (size_t)(t + 1) * kstep;
;             const char* a2 = last ? nA : cA + (size_t)(t + 2) * kstep; const char* b2 = last ? nB : cB + (size_t)(t + 2) * kstep;
;             const char* a3 = a2 + kstep; const char* b3 = b2 + kstep;
;             if constexpr (Epi::HOOK) { if (cur.ks < 0 && (t == 16 || t == 32)) E.hook(acc, cur, t >> 4, wr, wc, fr, fq); }
;             PG8_LDB(B0, 0, 0); PG8_LDB(B1, 0, 1); PG8_SCHED; PG8_LDA(At, 0, 0); PG8_STAGE(PG8_SA(1, 1), a1 + hstepA, voffA);
;             PG8_WAIT_V(8); PG8_WAIT_L(0); PG8_BAR; PG8_MMA(0, 0, At, B0); PG8_MMA(0, 1, At, B1); PG8_BAR; PG8_SCHED;
;             PG8_LDA(At, 0, 1); PG8_STAGE(PG8_SB(0, 0), b2, voffB); PG8_STAGE(PG8_SB(0, 1), b2 + hstepB, voffB); PG8_STAGE(PG8_SA(0, 0), a2, voffA);
;             PG8_WAIT_V(8); PG8_WAIT_L(0); PG8_BAR; PG8_MMA(1, 0, At, B0); PG8_MMA(1, 1, At, B1); PG8_BAR; PG8_SCHED;
.LBB0_906:
	s_add_i32 s23, s18, 2
	s_add_u32 s4, s40, 0x100
	s_addc_u32 s5, s41, 0
	s_cmp_eq_u32 s97, s18
	s_cselect_b32 s19, s79, s5
	s_cselect_b32 s18, s26, s4
	s_cselect_b32 s9, s27, s67
	s_cselect_b32 s8, s80, s66
	s_add_i32 s85, 0, 0x10000
	v_add_u32_e32 v2, s85, v162
	s_add_i32 vcc_lo, 0, 0x14000
	ds_read_b128 v[134:137], v2
	ds_read_b128 v[138:141], v2 offset:1024
	ds_read_b128 v[166:169], v2 offset:2048
	ds_read_b128 v[170:173], v2 offset:3072
	v_add_u32_e32 v2, vcc_lo, v162
	ds_read_b128 v[174:177], v2
	ds_read_b128 v[178:181], v2 offset:1024
	ds_read_b128 v[182:185], v2 offset:2048
	ds_read_b128 v[186:189], v2 offset:3072
	s_add_i32 m0, s39, 0xc000
	ds_read_b128 v[190:193], v164
	ds_read_b128 v[204:207], v164 offset:1024
	ds_read_b128 v[208:211], v164 offset:2048
	ds_read_b128 v[212:215], v164 offset:3072
	ds_read_b128 v[230:233], v164 offset:4096
	ds_read_b128 v[234:237], v164 offset:5120
	ds_read_b128 v[238:241], v164 offset:6144
	global_load_lds_dwordx4 v156, s[40:41]
	s_add_i32 m0, s39, 0xe000
	ds_read_b128 v[242:245], v164 offset:7168
	global_load_lds_dwordx4 v154, s[40:41]
	s_waitcnt vmcnt(8)
	s_waitcnt lgkmcnt(0)
	s_barrier
	s_setprio 1
	s_waitcnt lgkmcnt(0)
	v_mfma_f32_16x16x32_bf16 v[130:133], v[134:137], v[190:193], v[130:133]
	v_mfma_f32_16x16x32_bf16 v[126:129], v[166:169], v[190:193], v[126:129]
	v_mfma_f32_16x16x32_bf16 v[114:117], v[134:137], v[208:211], v[114:117]
	v_mfma_f32_16x16x32_bf16 v[110:113], v[166:169], v[208:211], v[110:113]
	v_mfma_f32_16x16x32_bf16 v[98:101], v[134:137], v[230:233], v[98:101]
	v_mfma_f32_16x16x32_bf16 v[94:97], v[166:169], v[230:233], v[94:97]
	v_mfma_f32_16x16x32_bf16 v[82:85], v[134:137], v[238:241], v[82:85]
	v_mfma_f32_16x16x32_bf16 v[78:81], v[166:169], v[238:241], v[78:81]
	v_mfma_f32_16x16x32_bf16 v[130:133], v[138:141], v[204:207], v[130:133]
	v_mfma_f32_16x16x32_bf16 v[126:129], v[170:173], v[204:207], v[126:129]
	v_mfma_f32_16x16x32_bf16 v[114:117], v[138:141], v[212:215], v[114:117]
	v_mfma_f32_16x16x32_bf16 v[110:113], v[170:173], v[212:215], v[110:113]
	v_mfma_f32_16x16x32_bf16 v[98:101], v[138:141], v[234:237], v[98:101]
	v_mfma_f32_16x16x32_bf16 v[94:97], v[170:173], v[234:237], v[94:97]
	v_mfma_f32_16x16x32_bf16 v[82:85], v[138:141], v[242:245], v[82:85]
	v_mfma_f32_16x16x32_bf16 v[78:81], v[170:173], v[242:245], v[78:81]
	s_setprio 0
	s_setprio 1
	v_mfma_f32_16x16x32_bf16 v[122:125], v[174:177], v[190:193], v[122:125]
	v_mfma_f32_16x16x32_bf16 v[118:121], v[182:185], v[190:193], v[118:121]
	v_mfma_f32_16x16x32_bf16 v[106:109], v[174:177], v[208:211], v[106:109]
	v_mfma_f32_16x16x32_bf16 v[102:105], v[182:185], v[208:211], v[102:105]
	v_mfma_f32_16x16x32_bf16 v[90:93], v[174:177], v[230:233], v[90:93]
	v_mfma_f32_16x16x32_bf16 v[86:89], v[182:185], v[230:233], v[86:89]
	v_mfma_f32_16x16x32_bf16 v[74:77], v[174:177], v[238:241], v[74:77]
	v_mfma_f32_16x16x32_bf16 v[70:73], v[182:185], v[238:241], v[70:73]
	v_mfma_f32_16x16x32_bf16 v[122:125], v[178:181], v[204:207], v[122:125]
	v_mfma_f32_16x16x32_bf16 v[118:121], v[186:189], v[204:207], v[118:121]
	v_mfma_f32_16x16x32_bf16 v[106:109], v[178:181], v[212:215], v[106:109]
	v_mfma_f32_16x16x32_bf16 v[102:105], v[186:189], v[212:215], v[102:105]
	v_mfma_f32_16x16x32_bf16 v[90:93], v[178:181], v[234:237], v[90:93]
	v_mfma_f32_16x16x32_bf16 v[86:89], v[186:189], v[234:237], v[86:89]
	v_mfma_f32_16x16x32_bf16 v[74:77], v[178:181], v[242:245], v[74:77]
	v_mfma_f32_16x16x32_bf16 v[70:73], v[186:189], v[242:245], v[70:73]
	s_setprio 0
	s_barrier
	s_add_i32 s40, s85, s38
	s_mov_b32 m0, s40
	ds_read_b128 v[190:193], v164 offset:16384
	ds_read_b128 v[204:207], v164 offset:17408
	ds_read_b128 v[208:211], v164 offset:18432
	ds_read_b128 v[212:215], v164 offset:19456
	global_load_lds_dwordx4 v144, s[8:9]
	s_add_i32 m0, s40, 0x2000
	s_add_u32 s40, s8, 0xc0000
	s_addc_u32 s41, s9, 0
	s_add_i32 s85, vcc_lo, s38
	global_load_lds_dwordx4 v148, s[8:9]
	s_mov_b32 m0, s85
	ds_read_b128 v[242:245], v164 offset:23552
	global_load_lds_dwordx4 v144, s[40:41]
	s_add_i32 m0, s85, 0x2000
	ds_read_b128 v[238:241], v164 offset:22528
	global_load_lds_dwordx4 v148, s[40:41]
	s_add_u32 s98, s18, 0x80
	s_addc_u32 s99, s19, 0
	s_mov_b32 m0, s39
	ds_read_b128 v[234:237], v164 offset:21504
	global_load_lds_dwordx4 v142, s[18:19]
	s_mov_b32 m0, s63
	ds_read_b128 v[230:233], v164 offset:20480
	global_load_lds_dwordx4 v146, s[18:19]
	s_waitcnt vmcnt(8)
	s_waitcnt lgkmcnt(0)
	s_barrier
	s_setprio 1
	s_waitcnt lgkmcnt(0)
	v_mfma_f32_16x16x32_bf16 v[66:69], v[134:137], v[190:193], v[66:69]
	v_mfma_f32_16x16x32_bf16 v[62:65], v[166:169], v[190:193], v[62:65]
	v_mfma_f32_16x16x32_bf16 v[50:53], v[134:137], v[208:211], v[50:53]
	v_mfma_f32_16x16x32_bf16 v[46:49], v[166:169], v[208:211], v[46:49]
	v_mfma_f32_16x16x32_bf16 v[34:37], v[134:137], v[230:233], v[34:37]
	v_mfma_f32_16x16x32_bf16 v[30:33], v[166:169], v[230:233], v[30:33]
	v_mfma_f32_16x16x32_bf16 v[18:21], v[134:137], v[238:241], v[18:21]
	v_mfma_f32_16x16x32_bf16 v[14:17], v[166:169], v[238:241], v[14:17]
	v_mfma_f32_16x16x32_bf16 v[66:69], v[138:141], v[204:207], v[66:69]
	v_mfma_f32_16x16x32_bf16 v[62:65], v[170:173], v[204:207], v[62:65]
	v_mfma_f32_16x16x32_bf16 v[50:53], v[138:141], v[212:215], v[50:53]
	v_mfma_f32_16x16x32_bf16 v[46:49], v[170:173], v[212:215], v[46:49]
	v_mfma_f32_16x16x32_bf16 v[34:37], v[138:141], v[234:237], v[34:37]
	v_mfma_f32_16x16x32_bf16 v[30:33], v[170:173], v[234:237], v[30:33]
	v_mfma_f32_16x16x32_bf16 v[18:21], v[138:141], v[242:245], v[18:21]
	v_mfma_f32_16x16x32_bf16 v[14:17], v[170:173], v[242:245], v[14:17]
	s_setprio 0
	s_setprio 1
	v_mfma_f32_16x16x32_bf16 v[58:61], v[174:177], v[190:193], v[58:61]
	v_mfma_f32_16x16x32_bf16 v[54:57], v[182:185], v[190:193], v[54:57]
	v_mfma_f32_16x16x32_bf16 v[42:45], v[174:177], v[208:211], v[42:45]
	v_mfma_f32_16x16x32_bf16 v[38:41], v[182:185], v[208:211], v[38:41]
	v_mfma_f32_16x16x32_bf16 v[26:29], v[174:177], v[230:233], v[26:29]
	v_mfma_f32_16x16x32_bf16 v[22:25], v[182:185], v[230:233], v[22:25]
	v_mfma_f32_16x16x32_bf16 v[10:13], v[174:177], v[238:241], v[10:13]
	v_mfma_f32_16x16x32_bf16 v[4:7], v[182:185], v[238:241], v[6:9]
	v_mfma_f32_16x16x32_bf16 v[58:61], v[178:181], v[204:207], v[58:61]
	v_mfma_f32_16x16x32_bf16 v[54:57], v[186:189], v[204:207], v[54:57]
	v_mfma_f32_16x16x32_bf16 v[42:45], v[178:181], v[212:215], v[42:45]
	v_mfma_f32_16x16x32_bf16 v[38:41], v[186:189], v[212:215], v[38:41]
	v_mfma_f32_16x16x32_bf16 v[26:29], v[178:181], v[234:237], v[26:29]
	v_mfma_f32_16x16x32_bf16 v[22:25], v[186:189], v[234:237], v[22:25]
	v_mfma_f32_16x16x32_bf16 v[10:13], v[178:181], v[242:245], v[10:13]
	v_mfma_f32_16x16x32_bf16 v[4:7], v[186:189], v[242:245], v[4:7]
	s_setprio 0
	s_barrier
; #define PG8_STAGE(bufoff, gbase, voff) do { _Pragma("unroll") for (int _i = 0; _i < 2; ++_i) \
;         __builtin_amdgcn_global_load_lds((const unsigned*)((const char*)(gbase) + (voff)[_i]), (LAS unsigned*)(lds + (bufoff) + ldsw + _i * 8192), 16, 0, 0); } while (0)
; #define PG8_LDA(dst, b, h) do { _Pragma("unroll") for (int m = 0; m < 4; ++m) _Pragma("unroll") for (int k = 0; k < 2; ++k) dst[m][k] = *(const LAS bf16x8*)(lds + PG8_SA(b, h) + aoff + m * 2048 + k * 1024); } while (0)
; #define PG8_LDB(dst, b, h) do { _Pragma("unroll") for (int n = 0; n < 2; ++n) _Pragma("unroll") for (int k = 0; k < 2; ++k) dst[n][k] = *(const LAS bf16x8*)(lds + PG8_SB(b, h) + boff + n * 2048 + k * 1024); } while (0)
; #define PG8_MMA(ai, bj, At, Bt) do { __builtin_amdgcn_s_setprio(1); _Pragma("unroll") for (int m = 0; m < 4; ++m) _Pragma("unroll") for (int n = 0; n < 2; ++n) _Pragma("unroll") for (int k = 0; k < 2; ++k) \
;         acc[ai][bj][m][n] = __builtin_amdgcn_mfma_f32_16x16x32_bf16(Bt[n][k], At[m][k], acc[ai][bj][m][n], 0, 0, 0); __builtin_amdgcn_s_setprio(0); } while (0)
; #define PG8_WAIT_V(n) asm volatile("s_waitcnt vmcnt(" #n ")" ::: "memory")
; #define PG8_WAIT_L(n) asm volatile("s_waitcnt lgkmcnt(" #n ")" ::: "memory")
; #define PG8_BAR __builtin_amdgcn_s_barrier()
; #define PG8_SCHED __builtin_amdgcn_sched_barrier(0)
; template <class Epi, class Sched>
; DI void gemm_phase(LAS unsigned char* lds, const Sched& S, const Epi& E) {
;     ...
;             PG8_LDB(B0, 1, 0); PG8_LDB(B1, 1, 1); PG8_SCHED; PG8_LDA(At, 1, 0); PG8_STAGE(PG8_SA(0, 1), a2 + hstepA, voffA);
;             PG8_WAIT_V(8); PG8_WAIT_L(0); PG8_BAR; PG8_MMA(0, 0, At, B0); PG8_MMA(0, 1, At, B1); PG8_BAR; PG8_SCHED;
;             PG8_LDA(At, 1, 1); PG8_STAGE(PG8_SB(1, 0), b3, voffB); PG8_STAGE(PG8_SB(1, 1), b3 + hstepB, voffB); PG8_STAGE(PG8_SA(1, 0), a3, voffA);
;             PG8_WAIT_V(8); PG8_WAIT_L(0); PG8_BAR; PG8_MMA(1, 0, At, B0); PG8_MMA(1, 1, At, B1); PG8_BAR; PG8_SCHED;
;         }
	s_add_i32 s40, 0, 0x18000
	v_add_u32_e32 v2, s40, v162
	s_add_i32 s41, 0, 0x1c000
	ds_read_b128 v[134:137], v2
	ds_read_b128 v[138:141], v2 offset:1024
	ds_read_b128 v[166:169], v2 offset:2048
	ds_read_b128 v[170:173], v2 offset:3072
	v_add_u32_e32 v2, s41, v162
	ds_read_b128 v[174:177], v2
	ds_read_b128 v[178:181], v2 offset:1024
	ds_read_b128 v[182:185], v2 offset:2048
	ds_read_b128 v[186:189], v2 offset:3072
	s_add_u32 s18, s18, 0xc0000
	s_addc_u32 s19, s19, 0
	s_mov_b32 m0, s64
	ds_read_b128 v[190:193], v164 offset:32768
	ds_read_b128 v[204:207], v164 offset:33792
	ds_read_b128 v[208:211], v164 offset:34816
	ds_read_b128 v[212:215], v164 offset:35840
	ds_read_b128 v[230:233], v164 offset:36864
	ds_read_b128 v[234:237], v164 offset:37888
	ds_read_b128 v[238:241], v164 offset:38912
	global_load_lds_dwordx4 v142, s[18:19]
	s_mov_b32 m0, s65
	ds_read_b128 v[242:245], v164 offset:39936
	global_load_lds_dwordx4 v146, s[18:19]
	s_waitcnt vmcnt(8)
	s_waitcnt lgkmcnt(0)
	s_barrier
	s_setprio 1
	s_waitcnt lgkmcnt(0)
	v_mfma_f32_16x16x32_bf16 v[130:133], v[134:137], v[190:193], v[130:133]
	v_mfma_f32_16x16x32_bf16 v[126:129], v[166:169], v[190:193], v[126:129]
	v_mfma_f32_16x16x32_bf16 v[114:117], v[134:137], v[208:211], v[114:117]
	v_mfma_f32_16x16x32_bf16 v[110:113], v[166:169], v[208:211], v[110:113]
	v_mfma_f32_16x16x32_bf16 v[98:101], v[134:137], v[230:233], v[98:101]
	v_mfma_f32_16x16x32_bf16 v[94:97], v[166:169], v[230:233], v[94:97]
	v_mfma_f32_16x16x32_bf16 v[82:85], v[134:137], v[238:241], v[82:85]
	v_mfma_f32_16x16x32_bf16 v[78:81], v[166:169], v[238:241], v[78:81]
	v_mfma_f32_16x16x32_bf16 v[130:133], v[138:141], v[204:207], v[130:133]
	v_mfma_f32_16x16x32_bf16 v[126:129], v[170:173], v[204:207], v[126:129]
	v_mfma_f32_16x16x32_bf16 v[114:117], v[138:141], v[212:215], v[114:117]
	v_mfma_f32_16x16x32_bf16 v[110:113], v[170:173], v[212:215], v[110:113]
	v_mfma_f32_16x16x32_bf16 v[98:101], v[138:141], v[234:237], v[98:101]
	v_mfma_f32_16x16x32_bf16 v[94:97], v[170:173], v[234:237], v[94:97]
	v_mfma_f32_16x16x32_bf16 v[82:85], v[138:141], v[242:245], v[82:85]
	v_mfma_f32_16x16x32_bf16 v[78:81], v[170:173], v[242:245], v[78:81]
	s_setprio 0
	s_setprio 1
	v_mfma_f32_16x16x32_bf16 v[122:125], v[174:177], v[190:193], v[122:125]
	v_mfma_f32_16x16x32_bf16 v[118:121], v[182:185], v[190:193], v[118:121]
	v_mfma_f32_16x16x32_bf16 v[106:109], v[174:177], v[208:211], v[106:109]
	v_mfma_f32_16x16x32_bf16 v[102:105], v[182:185], v[208:211], v[102:105]
	v_mfma_f32_16x16x32_bf16 v[90:93], v[174:177], v[230:233], v[90:93]
	v_mfma_f32_16x16x32_bf16 v[86:89], v[182:185], v[230:233], v[86:89]
	v_mfma_f32_16x16x32_bf16 v[74:77], v[174:177], v[238:241], v[74:77]
	v_mfma_f32_16x16x32_bf16 v[70:73], v[182:185], v[238:241], v[70:73]
	v_mfma_f32_16x16x32_bf16 v[122:125], v[178:181], v[204:207], v[122:125]
	v_mfma_f32_16x16x32_bf16 v[118:121], v[186:189], v[204:207], v[118:121]
	v_mfma_f32_16x16x32_bf16 v[106:109], v[178:181], v[212:215], v[106:109]
	v_mfma_f32_16x16x32_bf16 v[102:105], v[186:189], v[212:215], v[102:105]
	v_mfma_f32_16x16x32_bf16 v[90:93], v[178:181], v[234:237], v[90:93]
	v_mfma_f32_16x16x32_bf16 v[86:89], v[186:189], v[234:237], v[86:89]
	v_mfma_f32_16x16x32_bf16 v[74:77], v[178:181], v[242:245], v[74:77]
	v_mfma_f32_16x16x32_bf16 v[70:73], v[186:189], v[242:245], v[70:73]
	s_setprio 0
	s_barrier
	s_add_i32 s18, s40, s38
	s_add_u32 s8, s8, 0x80
	s_addc_u32 s9, s9, 0
	s_mov_b32 m0, s18
	ds_read_b128 v[190:193], v164 offset:49152
	ds_read_b128 v[204:207], v164 offset:50176
	ds_read_b128 v[208:211], v164 offset:51200
	ds_read_b128 v[212:215], v164 offset:52224
	global_load_lds_dwordx4 v144, s[8:9]
	s_add_i32 m0, s18, 0x2000
	s_add_i32 s18, s41, s38
	global_load_lds_dwordx4 v148, s[8:9]
	s_add_u32 s8, s8, 0xc0000
	s_addc_u32 s9, s9, 0
	s_mov_b32 m0, s18
	ds_read_b128 v[242:245], v164 offset:56320
	global_load_lds_dwordx4 v144, s[8:9]
	s_add_i32 m0, s18, 0x2000
	ds_read_b128 v[238:241], v164 offset:55296
	global_load_lds_dwordx4 v148, s[8:9]
	s_mov_b32 m0, s75
	ds_read_b128 v[234:237], v164 offset:54272
	global_load_lds_dwordx4 v142, s[98:99]
	s_mov_b32 m0, s81
	ds_read_b128 v[230:233], v164 offset:53248
	global_load_lds_dwordx4 v146, s[98:99]
	s_waitcnt vmcnt(8)
	s_waitcnt lgkmcnt(0)
	s_barrier
	s_setprio 1
	s_waitcnt lgkmcnt(0)
	v_mfma_f32_16x16x32_bf16 v[66:69], v[134:137], v[190:193], v[66:69]
	v_mfma_f32_16x16x32_bf16 v[62:65], v[166:169], v[190:193], v[62:65]
	v_mfma_f32_16x16x32_bf16 v[50:53], v[134:137], v[208:211], v[50:53]
	v_mfma_f32_16x16x32_bf16 v[46:49], v[166:169], v[208:211], v[46:49]
	v_mfma_f32_16x16x32_bf16 v[34:37], v[134:137], v[230:233], v[34:37]
	v_mfma_f32_16x16x32_bf16 v[30:33], v[166:169], v[230:233], v[30:33]
	v_mfma_f32_16x16x32_bf16 v[18:21], v[134:137], v[238:241], v[18:21]
	v_mfma_f32_16x16x32_bf16 v[14:17], v[166:169], v[238:241], v[14:17]
	v_mfma_f32_16x16x32_bf16 v[66:69], v[138:141], v[204:207], v[66:69]
	v_mfma_f32_16x16x32_bf16 v[62:65], v[170:173], v[204:207], v[62:65]
	v_mfma_f32_16x16x32_bf16 v[50:53], v[138:141], v[212:215], v[50:53]
	v_mfma_f32_16x16x32_bf16 v[46:49], v[170:173], v[212:215], v[46:49]
	v_mfma_f32_16x16x32_bf16 v[34:37], v[138:141], v[234:237], v[34:37]
	v_mfma_f32_16x16x32_bf16 v[30:33], v[170:173], v[234:237], v[30:33]
	v_mfma_f32_16x16x32_bf16 v[18:21], v[138:141], v[242:245], v[18:21]
	v_mfma_f32_16x16x32_bf16 v[14:17], v[170:173], v[242:245], v[14:17]
	s_setprio 0
	s_setprio 1
	v_mfma_f32_16x16x32_bf16 v[58:61], v[174:177], v[190:193], v[58:61]
	v_mfma_f32_16x16x32_bf16 v[54:57], v[182:185], v[190:193], v[54:57]
	v_mfma_f32_16x16x32_bf16 v[42:45], v[174:177], v[208:211], v[42:45]
	v_mfma_f32_16x16x32_bf16 v[38:41], v[182:185], v[208:211], v[38:41]
	v_mfma_f32_16x16x32_bf16 v[26:29], v[174:177], v[230:233], v[26:29]
	v_mfma_f32_16x16x32_bf16 v[22:25], v[182:185], v[230:233], v[22:25]
	v_mfma_f32_16x16x32_bf16 v[8:11], v[174:177], v[238:241], v[10:13]
	v_mfma_f32_16x16x32_bf16 v[4:7], v[182:185], v[238:241], v[4:7]
	v_mfma_f32_16x16x32_bf16 v[58:61], v[178:181], v[204:207], v[58:61]
	v_mfma_f32_16x16x32_bf16 v[54:57], v[186:189], v[204:207], v[54:57]
	v_mfma_f32_16x16x32_bf16 v[42:45], v[178:181], v[212:215], v[42:45]
	v_mfma_f32_16x16x32_bf16 v[38:41], v[186:189], v[212:215], v[38:41]
	v_mfma_f32_16x16x32_bf16 v[26:29], v[178:181], v[234:237], v[26:29]
	v_mfma_f32_16x16x32_bf16 v[22:25], v[186:189], v[234:237], v[22:25]
	v_mfma_f32_16x16x32_bf16 v[10:13], v[178:181], v[242:245], v[8:11]
	v_mfma_f32_16x16x32_bf16 v[6:9], v[186:189], v[242:245], v[4:7]
	s_setprio 0
	s_barrier
	s_add_i32 s22, s22, 1
	s_add_u32 s66, s66, 0x100
	s_addc_u32 s67, s67, 0
	s_cmp_ge_i32 s23, s10
	s_cbranch_scc1 .LBB0_908
	s_mov_b64 s[40:41], s[4:5]
	s_mov_b32 s18, s23
	s_andn2_b64 vcc, exec, s[56:57]
	s_cbranch_vccnz .LBB0_906
	s_branch .LBB0_900

; #define PG8_STAGE(bufoff, gbase, voff) do { _Pragma("unroll") for (int _i = 0; _i < 2; ++_i) \
;         __builtin_amdgcn_global_load_lds((const unsigned*)((const char*)(gbase) + (voff)[_i]), (LAS unsigned*)(lds + (bufoff) + ldsw + _i * 8192), 16, 0, 0); } while (0)
; #define PG8_LDA(dst, b, h) do { _Pragma("unroll") for (int m = 0; m < 4; ++m) _Pragma("unroll") for (int k = 0; k < 2; ++k) dst[m][k] = *(const LAS bf16x8*)(lds + PG8_SA(b, h) + aoff + m * 2048 + k * 1024); } while (0)
; #define PG8_LDB(dst, b, h) do { _Pragma("unroll") for (int n = 0; n < 2; ++n) _Pragma("unroll") for (int k = 0; k < 2; ++k) dst[n][k] = *(const LAS bf16x8*)(lds + PG8_SB(b, h) + boff + n * 2048 + k * 1024); } while (0)
; #define PG8_MMA(ai, bj, At, Bt) do { __builtin_amdgcn_s_setprio(1); _Pragma("unroll") for (int m = 0; m < 4; ++m) _Pragma("unroll") for (int n = 0; n < 2; ++n) _Pragma("unroll") for (int k = 0; k < 2; ++k) \
;         acc[ai][bj][m][n] = __builtin_amdgcn_mfma_f32_16x16x32_bf16(Bt[n][k], At[m][k], acc[ai][bj][m][n], 0, 0, 0); __builtin_amdgcn_s_setprio(0); } while (0)
; #define PG8_WAIT_V(n) asm volatile("s_waitcnt vmcnt(" #n ")" ::: "memory")
; #define PG8_WAIT_L(n) asm volatile("s_waitcnt lgkmcnt(" #n ")" ::: "memory")
; #define PG8_BAR __builtin_amdgcn_s_barrier()
; template <class Epi, class Sched>
; DI void gemm_phase(LAS unsigned char* lds, const Sched& S, const Epi& E) {
;     ...
;         for (int t = 0; t < nt; t += 2) {
;             const bool last = (t == nt - 2);
;             const char* a1 = cA + (size_t)(t + 1) * kstep;
;             const char* a2 = last ? nA : cA + (size_t)(t + 2) * kstep; const char* b2 = last ? nB : cB + (size_t)(t + 2) * kstep;
;             const char* a3 = a2 + kstep; const char* b3 = b2 + kstep;
;             if constexpr (Epi::HOOK) { if (cur.ks < 0 && (t == 16 || t == 32)) E.hook(acc, cur, t >> 4, wr, wc, fr, fq); }
;             PG8_LDB(B0, 0, 0); PG8_LDB(B1, 0, 1); PG8_SCHED; PG8_LDA(At, 0, 0); PG8_STAGE(PG8_SA(1, 1), a1 + hstepA, voffA);
;             PG8_WAIT_V(8); PG8_WAIT_L(0); PG8_BAR; PG8_MMA(0, 0, At, B0); PG8_MMA(0, 1, At, B1); PG8_BAR; PG8_SCHED;
;             PG8_LDA(At, 0, 1); PG8_STAGE(PG8_SB(0, 0), b2, voffB); PG8_STAGE(PG8_SB(0, 1), b2 + hstepB, voffB); PG8_STAGE(PG8_SA(0, 0), a2, voffA);
;             PG8_WAIT_V(8); PG8_WAIT_L(0); PG8_BAR; PG8_MMA(1, 0, At, B0); PG8_MMA(1, 1, At, B1); PG8_BAR; PG8_SCHED;
.LBB0_1104:
	s_add_i32 s82, s52, 2
	s_add_u32 s53, s42, 0xfff80080
	s_addc_u32 s54, s43, -1
	s_add_i32 s83, 0, 0x10000
	s_cmp_eq_u32 s79, s52
	s_cselect_b32 s55, s56, s54
	s_cselect_b32 s54, s57, s53
	s_cselect_b32 s53, s58, s81
	s_cselect_b32 s52, s59, s80
	s_add_i32 s85, 0, 0x14000
	s_waitcnt vmcnt(0)
	v_add_u32_e32 v112, s83, v197
	v_add_u32_e32 v160, s85, v197
	ds_read_b128 v[84:87], v112
	ds_read_b128 v[88:91], v112 offset:1024
	ds_read_b128 v[104:107], v112 offset:2048
	ds_read_b128 v[112:115], v112 offset:3072
	ds_read_b128 v[124:127], v160
	ds_read_b128 v[136:139], v160 offset:1024
	ds_read_b128 v[148:151], v160 offset:2048
	ds_read_b128 v[160:163], v160 offset:3072
	s_add_i32 m0, s26, 0xc000
	ds_read_b128 v[164:167], v231
	ds_read_b128 v[168:171], v231 offset:1024
	ds_read_b128 v[172:175], v231 offset:2048
	ds_read_b128 v[176:179], v231 offset:3072
	ds_read_b128 v[180:183], v231 offset:4096
	ds_read_b128 v[184:187], v231 offset:5120
	ds_read_b128 v[188:191], v231 offset:6144
	global_load_lds_dwordx4 v212, s[42:43]
	s_add_i32 m0, s26, 0xe000
	ds_read_b128 v[192:195], v231 offset:7168
	global_load_lds_dwordx4 v210, s[42:43]
	s_waitcnt vmcnt(8)
	s_waitcnt lgkmcnt(0)
	s_barrier
	s_setprio 1
	s_waitcnt lgkmcnt(0)
	v_mfma_f32_16x16x32_bf16 v[156:159], v[84:87], v[164:167], v[156:159]
	v_mfma_f32_16x16x32_bf16 v[152:155], v[104:107], v[164:167], v[152:155]
	v_mfma_f32_16x16x32_bf16 v[132:135], v[84:87], v[172:175], v[132:135]
	v_mfma_f32_16x16x32_bf16 v[128:131], v[104:107], v[172:175], v[128:131]
	v_mfma_f32_16x16x32_bf16 v[108:111], v[84:87], v[180:183], v[108:111]
	v_mfma_f32_16x16x32_bf16 v[100:103], v[104:107], v[180:183], v[100:103]
	v_mfma_f32_16x16x32_bf16 v[80:83], v[84:87], v[188:191], v[80:83]
	v_mfma_f32_16x16x32_bf16 v[76:79], v[104:107], v[188:191], v[76:79]
	v_mfma_f32_16x16x32_bf16 v[156:159], v[88:91], v[168:171], v[156:159]
	v_mfma_f32_16x16x32_bf16 v[152:155], v[112:115], v[168:171], v[152:155]
	v_mfma_f32_16x16x32_bf16 v[132:135], v[88:91], v[176:179], v[132:135]
	v_mfma_f32_16x16x32_bf16 v[128:131], v[112:115], v[176:179], v[128:131]
	v_mfma_f32_16x16x32_bf16 v[108:111], v[88:91], v[184:187], v[108:111]
	v_mfma_f32_16x16x32_bf16 v[100:103], v[112:115], v[184:187], v[100:103]
	v_mfma_f32_16x16x32_bf16 v[80:83], v[88:91], v[192:195], v[80:83]
	v_mfma_f32_16x16x32_bf16 v[76:79], v[112:115], v[192:195], v[76:79]
	s_setprio 0
	s_setprio 1
	v_mfma_f32_16x16x32_bf16 v[144:147], v[124:127], v[164:167], v[144:147]
	v_mfma_f32_16x16x32_bf16 v[140:143], v[148:151], v[164:167], v[140:143]
	v_mfma_f32_16x16x32_bf16 v[120:123], v[124:127], v[172:175], v[120:123]
	v_mfma_f32_16x16x32_bf16 v[116:119], v[148:151], v[172:175], v[116:119]
	v_mfma_f32_16x16x32_bf16 v[96:99], v[124:127], v[180:183], v[96:99]
	v_mfma_f32_16x16x32_bf16 v[92:95], v[148:151], v[180:183], v[92:95]
	v_mfma_f32_16x16x32_bf16 v[72:75], v[124:127], v[188:191], v[72:75]
	v_mfma_f32_16x16x32_bf16 v[68:71], v[148:151], v[188:191], v[68:71]
	v_mfma_f32_16x16x32_bf16 v[144:147], v[136:139], v[168:171], v[144:147]
	v_mfma_f32_16x16x32_bf16 v[140:143], v[160:163], v[168:171], v[140:143]
	v_mfma_f32_16x16x32_bf16 v[120:123], v[136:139], v[176:179], v[120:123]
	v_mfma_f32_16x16x32_bf16 v[116:119], v[160:163], v[176:179], v[116:119]
	v_mfma_f32_16x16x32_bf16 v[96:99], v[136:139], v[184:187], v[96:99]
	v_mfma_f32_16x16x32_bf16 v[92:95], v[160:163], v[184:187], v[92:95]
	v_mfma_f32_16x16x32_bf16 v[72:75], v[136:139], v[192:195], v[72:75]
	v_mfma_f32_16x16x32_bf16 v[68:71], v[160:163], v[192:195], v[68:71]
	s_setprio 0
	s_barrier
	s_add_i32 s83, s83, s23
	s_mov_b32 m0, s83
	ds_read_b128 v[164:167], v231 offset:16384
	ds_read_b128 v[168:171], v231 offset:17408
	ds_read_b128 v[172:175], v231 offset:18432
	ds_read_b128 v[176:179], v231 offset:19456
	global_load_lds_dwordx4 v2, s[52:53]
	s_add_i32 m0, s83, 0x2000
	s_add_u32 s86, s52, 0x80000
	s_addc_u32 s87, s53, 0
	s_add_i32 s83, s85, s23
	global_load_lds_dwordx4 v208, s[52:53]
	s_mov_b32 m0, s83
	ds_read_b128 v[192:195], v231 offset:23552
	global_load_lds_dwordx4 v2, s[86:87]
	s_add_i32 m0, s83, 0x2000
	ds_read_b128 v[188:191], v231 offset:22528
	global_load_lds_dwordx4 v208, s[86:87]
	s_add_u32 s98, s54, 0x80
	s_addc_u32 s99, s55, 0
	s_mov_b32 m0, s26
	ds_read_b128 v[184:187], v231 offset:21504
	global_load_lds_dwordx4 v204, s[54:55]
	s_mov_b32 m0, s27
	ds_read_b128 v[180:183], v231 offset:20480
	global_load_lds_dwordx4 v206, s[54:55]
	s_waitcnt vmcnt(8)
	s_waitcnt lgkmcnt(0)
	s_barrier
	s_setprio 1
	s_waitcnt lgkmcnt(0)
	v_mfma_f32_16x16x32_bf16 v[64:67], v[84:87], v[164:167], v[64:67]
	v_mfma_f32_16x16x32_bf16 v[60:63], v[104:107], v[164:167], v[60:63]
	v_mfma_f32_16x16x32_bf16 v[48:51], v[84:87], v[172:175], v[48:51]
	v_mfma_f32_16x16x32_bf16 v[44:47], v[104:107], v[172:175], v[44:47]
	v_mfma_f32_16x16x32_bf16 v[32:35], v[84:87], v[180:183], v[32:35]
	v_mfma_f32_16x16x32_bf16 v[28:31], v[104:107], v[180:183], v[28:31]
	v_mfma_f32_16x16x32_bf16 v[16:19], v[84:87], v[188:191], v[16:19]
	v_mfma_f32_16x16x32_bf16 v[12:15], v[104:107], v[188:191], v[12:15]
	v_mfma_f32_16x16x32_bf16 v[64:67], v[88:91], v[168:171], v[64:67]
	v_mfma_f32_16x16x32_bf16 v[60:63], v[112:115], v[168:171], v[60:63]
	v_mfma_f32_16x16x32_bf16 v[48:51], v[88:91], v[176:179], v[48:51]
	v_mfma_f32_16x16x32_bf16 v[44:47], v[112:115], v[176:179], v[44:47]
	v_mfma_f32_16x16x32_bf16 v[32:35], v[88:91], v[184:187], v[32:35]
	v_mfma_f32_16x16x32_bf16 v[28:31], v[112:115], v[184:187], v[28:31]
	v_mfma_f32_16x16x32_bf16 v[16:19], v[88:91], v[192:195], v[16:19]
	v_mfma_f32_16x16x32_bf16 v[12:15], v[112:115], v[192:195], v[12:15]
	s_setprio 0
	s_setprio 1
	v_mfma_f32_16x16x32_bf16 v[56:59], v[124:127], v[164:167], v[56:59]
	v_mfma_f32_16x16x32_bf16 v[52:55], v[148:151], v[164:167], v[52:55]
	v_mfma_f32_16x16x32_bf16 v[40:43], v[124:127], v[172:175], v[40:43]
	v_mfma_f32_16x16x32_bf16 v[36:39], v[148:151], v[172:175], v[36:39]
	v_mfma_f32_16x16x32_bf16 v[24:27], v[124:127], v[180:183], v[24:27]
	v_mfma_f32_16x16x32_bf16 v[20:23], v[148:151], v[180:183], v[20:23]
	v_mfma_f32_16x16x32_bf16 v[8:11], v[124:127], v[188:191], v[8:11]
	v_mfma_f32_16x16x32_bf16 v[4:7], v[148:151], v[188:191], v[4:7]
	v_mfma_f32_16x16x32_bf16 v[56:59], v[136:139], v[168:171], v[56:59]
	v_mfma_f32_16x16x32_bf16 v[52:55], v[160:163], v[168:171], v[52:55]
	v_mfma_f32_16x16x32_bf16 v[40:43], v[136:139], v[176:179], v[40:43]
	v_mfma_f32_16x16x32_bf16 v[36:39], v[160:163], v[176:179], v[36:39]
	v_mfma_f32_16x16x32_bf16 v[24:27], v[136:139], v[184:187], v[24:27]
	v_mfma_f32_16x16x32_bf16 v[20:23], v[160:163], v[184:187], v[20:23]
	v_mfma_f32_16x16x32_bf16 v[8:11], v[136:139], v[192:195], v[8:11]
	v_mfma_f32_16x16x32_bf16 v[4:7], v[160:163], v[192:195], v[4:7]
	s_setprio 0
	s_barrier
; #define PG8_STAGE(bufoff, gbase, voff) do { _Pragma("unroll") for (int _i = 0; _i < 2; ++_i) \
;         __builtin_amdgcn_global_load_lds((const unsigned*)((const char*)(gbase) + (voff)[_i]), (LAS unsigned*)(lds + (bufoff) + ldsw + _i * 8192), 16, 0, 0); } while (0)
; #define PG8_LDA(dst, b, h) do { _Pragma("unroll") for (int m = 0; m < 4; ++m) _Pragma("unroll") for (int k = 0; k < 2; ++k) dst[m][k] = *(const LAS bf16x8*)(lds + PG8_SA(b, h) + aoff + m * 2048 + k * 1024); } while (0)
; #define PG8_LDB(dst, b, h) do { _Pragma("unroll") for (int n = 0; n < 2; ++n) _Pragma("unroll") for (int k = 0; k < 2; ++k) dst[n][k] = *(const LAS bf16x8*)(lds + PG8_SB(b, h) + boff + n * 2048 + k * 1024); } while (0)
; #define PG8_MMA(ai, bj, At, Bt) do { __builtin_amdgcn_s_setprio(1); _Pragma("unroll") for (int m = 0; m < 4; ++m) _Pragma("unroll") for (int n = 0; n < 2; ++n) _Pragma("unroll") for (int k = 0; k < 2; ++k) \
;         acc[ai][bj][m][n] = __builtin_amdgcn_mfma_f32_16x16x32_bf16(Bt[n][k], At[m][k], acc[ai][bj][m][n], 0, 0, 0); __builtin_amdgcn_s_setprio(0); } while (0)
; #define PG8_WAIT_V(n) asm volatile("s_waitcnt vmcnt(" #n ")" ::: "memory")
; #define PG8_WAIT_L(n) asm volatile("s_waitcnt lgkmcnt(" #n ")" ::: "memory")
; #define PG8_BAR __builtin_amdgcn_s_barrier()
; #define PG8_SCHED __builtin_amdgcn_sched_barrier(0)
; template <class Epi, class Sched>
; DI void gemm_phase(LAS unsigned char* lds, const Sched& S, const Epi& E) {
;     ...
;             PG8_LDB(B0, 1, 0); PG8_LDB(B1, 1, 1); PG8_SCHED; PG8_LDA(At, 1, 0); PG8_STAGE(PG8_SA(0, 1), a2 + hstepA, voffA);
;             PG8_WAIT_V(8); PG8_WAIT_L(0); PG8_BAR; PG8_MMA(0, 0, At, B0); PG8_MMA(0, 1, At, B1); PG8_BAR; PG8_SCHED;
;             PG8_LDA(At, 1, 1); PG8_STAGE(PG8_SB(1, 0), b3, voffB); PG8_STAGE(PG8_SB(1, 1), b3 + hstepB, voffB); PG8_STAGE(PG8_SA(1, 0), a3, voffA);
;             PG8_WAIT_V(8); PG8_WAIT_L(0); PG8_BAR; PG8_MMA(1, 0, At, B0); PG8_MMA(1, 1, At, B1); PG8_BAR; PG8_SCHED;
;         }
;         if (wr == 0) PG8_BAR;
	s_add_i32 s83, 0, 0x18000
	s_add_i32 s85, 0, 0x1c000
	v_add_u32_e32 v112, s83, v197
	v_add_u32_e32 v160, s85, v197
	ds_read_b128 v[84:87], v112
	ds_read_b128 v[88:91], v112 offset:1024
	ds_read_b128 v[104:107], v112 offset:2048
	ds_read_b128 v[112:115], v112 offset:3072
	ds_read_b128 v[124:127], v160
	ds_read_b128 v[136:139], v160 offset:1024
	ds_read_b128 v[148:151], v160 offset:2048
	ds_read_b128 v[160:163], v160 offset:3072
	s_add_u32 s54, s54, 0x80000
	s_addc_u32 s55, s55, 0
	s_mov_b32 m0, s60
	ds_read_b128 v[164:167], v231 offset:32768
	ds_read_b128 v[168:171], v231 offset:33792
	ds_read_b128 v[172:175], v231 offset:34816
	ds_read_b128 v[176:179], v231 offset:35840
	ds_read_b128 v[180:183], v231 offset:36864
	ds_read_b128 v[184:187], v231 offset:37888
	ds_read_b128 v[188:191], v231 offset:38912
	global_load_lds_dwordx4 v204, s[54:55]
	s_mov_b32 m0, s61
	ds_read_b128 v[192:195], v231 offset:39936
	global_load_lds_dwordx4 v206, s[54:55]
	s_waitcnt vmcnt(8)
	s_waitcnt lgkmcnt(0)
	s_barrier
	s_setprio 1
	s_waitcnt lgkmcnt(0)
	v_mfma_f32_16x16x32_bf16 v[156:159], v[84:87], v[164:167], v[156:159]
	v_mfma_f32_16x16x32_bf16 v[152:155], v[104:107], v[164:167], v[152:155]
	v_mfma_f32_16x16x32_bf16 v[132:135], v[84:87], v[172:175], v[132:135]
	v_mfma_f32_16x16x32_bf16 v[128:131], v[104:107], v[172:175], v[128:131]
	v_mfma_f32_16x16x32_bf16 v[108:111], v[84:87], v[180:183], v[108:111]
	v_mfma_f32_16x16x32_bf16 v[100:103], v[104:107], v[180:183], v[100:103]
	v_mfma_f32_16x16x32_bf16 v[80:83], v[84:87], v[188:191], v[80:83]
	v_mfma_f32_16x16x32_bf16 v[76:79], v[104:107], v[188:191], v[76:79]
	v_mfma_f32_16x16x32_bf16 v[156:159], v[88:91], v[168:171], v[156:159]
	v_mfma_f32_16x16x32_bf16 v[152:155], v[112:115], v[168:171], v[152:155]
	v_mfma_f32_16x16x32_bf16 v[132:135], v[88:91], v[176:179], v[132:135]
	v_mfma_f32_16x16x32_bf16 v[128:131], v[112:115], v[176:179], v[128:131]
	v_mfma_f32_16x16x32_bf16 v[108:111], v[88:91], v[184:187], v[108:111]
	v_mfma_f32_16x16x32_bf16 v[100:103], v[112:115], v[184:187], v[100:103]
	v_mfma_f32_16x16x32_bf16 v[80:83], v[88:91], v[192:195], v[80:83]
	v_mfma_f32_16x16x32_bf16 v[76:79], v[112:115], v[192:195], v[76:79]
	s_setprio 0
	s_setprio 1
	v_mfma_f32_16x16x32_bf16 v[144:147], v[124:127], v[164:167], v[144:147]
	v_mfma_f32_16x16x32_bf16 v[140:143], v[148:151], v[164:167], v[140:143]
	v_mfma_f32_16x16x32_bf16 v[120:123], v[124:127], v[172:175], v[120:123]
	v_mfma_f32_16x16x32_bf16 v[116:119], v[148:151], v[172:175], v[116:119]
	v_mfma_f32_16x16x32_bf16 v[96:99], v[124:127], v[180:183], v[96:99]
	v_mfma_f32_16x16x32_bf16 v[92:95], v[148:151], v[180:183], v[92:95]
	v_mfma_f32_16x16x32_bf16 v[72:75], v[124:127], v[188:191], v[72:75]
	v_mfma_f32_16x16x32_bf16 v[68:71], v[148:151], v[188:191], v[68:71]
	v_mfma_f32_16x16x32_bf16 v[144:147], v[136:139], v[168:171], v[144:147]
	v_mfma_f32_16x16x32_bf16 v[140:143], v[160:163], v[168:171], v[140:143]
	v_mfma_f32_16x16x32_bf16 v[120:123], v[136:139], v[176:179], v[120:123]
	v_mfma_f32_16x16x32_bf16 v[116:119], v[160:163], v[176:179], v[116:119]
	v_mfma_f32_16x16x32_bf16 v[96:99], v[136:139], v[184:187], v[96:99]
	v_mfma_f32_16x16x32_bf16 v[92:95], v[160:163], v[184:187], v[92:95]
	v_mfma_f32_16x16x32_bf16 v[72:75], v[136:139], v[192:195], v[72:75]
	v_mfma_f32_16x16x32_bf16 v[68:71], v[160:163], v[192:195], v[68:71]
	s_setprio 0
	s_barrier
	s_add_i32 s54, s83, s23
	s_add_u32 s52, s52, 0x80
	s_addc_u32 s53, s53, 0
	s_mov_b32 m0, s54
	ds_read_b128 v[164:167], v231 offset:49152
	ds_read_b128 v[168:171], v231 offset:50176
	ds_read_b128 v[172:175], v231 offset:51200
	ds_read_b128 v[176:179], v231 offset:52224
	global_load_lds_dwordx4 v2, s[52:53]
	s_add_i32 m0, s54, 0x2000
	s_add_i32 s54, s85, s23
	global_load_lds_dwordx4 v208, s[52:53]
	s_add_u32 s52, s52, 0x80000
	s_addc_u32 s53, s53, 0
	s_mov_b32 m0, s54
	ds_read_b128 v[192:195], v231 offset:56320
	global_load_lds_dwordx4 v2, s[52:53]
	s_add_i32 m0, s54, 0x2000
	ds_read_b128 v[188:191], v231 offset:55296
	global_load_lds_dwordx4 v208, s[52:53]
	s_mov_b32 m0, s71
	ds_read_b128 v[184:187], v231 offset:54272
	global_load_lds_dwordx4 v204, s[98:99]
	s_mov_b32 m0, s72
	ds_read_b128 v[180:183], v231 offset:53248
	global_load_lds_dwordx4 v206, s[98:99]
	s_waitcnt vmcnt(8)
	s_waitcnt lgkmcnt(0)
	s_barrier
	s_setprio 1
	s_waitcnt lgkmcnt(0)
	v_mfma_f32_16x16x32_bf16 v[64:67], v[84:87], v[164:167], v[64:67]
	v_mfma_f32_16x16x32_bf16 v[60:63], v[104:107], v[164:167], v[60:63]
	v_mfma_f32_16x16x32_bf16 v[48:51], v[84:87], v[172:175], v[48:51]
	v_mfma_f32_16x16x32_bf16 v[44:47], v[104:107], v[172:175], v[44:47]
	v_mfma_f32_16x16x32_bf16 v[32:35], v[84:87], v[180:183], v[32:35]
	v_mfma_f32_16x16x32_bf16 v[28:31], v[104:107], v[180:183], v[28:31]
	v_mfma_f32_16x16x32_bf16 v[16:19], v[84:87], v[188:191], v[16:19]
	v_mfma_f32_16x16x32_bf16 v[12:15], v[104:107], v[188:191], v[12:15]
	v_mfma_f32_16x16x32_bf16 v[64:67], v[88:91], v[168:171], v[64:67]
	v_mfma_f32_16x16x32_bf16 v[60:63], v[112:115], v[168:171], v[60:63]
	v_mfma_f32_16x16x32_bf16 v[48:51], v[88:91], v[176:179], v[48:51]
	v_mfma_f32_16x16x32_bf16 v[44:47], v[112:115], v[176:179], v[44:47]
	v_mfma_f32_16x16x32_bf16 v[32:35], v[88:91], v[184:187], v[32:35]
	v_mfma_f32_16x16x32_bf16 v[28:31], v[112:115], v[184:187], v[28:31]
	v_mfma_f32_16x16x32_bf16 v[16:19], v[88:91], v[192:195], v[16:19]
	v_mfma_f32_16x16x32_bf16 v[12:15], v[112:115], v[192:195], v[12:15]
	s_setprio 0
	s_setprio 1
	v_mfma_f32_16x16x32_bf16 v[56:59], v[124:127], v[164:167], v[56:59]
	v_mfma_f32_16x16x32_bf16 v[52:55], v[148:151], v[164:167], v[52:55]
	v_mfma_f32_16x16x32_bf16 v[40:43], v[124:127], v[172:175], v[40:43]
	v_mfma_f32_16x16x32_bf16 v[36:39], v[148:151], v[172:175], v[36:39]
	v_mfma_f32_16x16x32_bf16 v[24:27], v[124:127], v[180:183], v[24:27]
	v_mfma_f32_16x16x32_bf16 v[20:23], v[148:151], v[180:183], v[20:23]
	v_mfma_f32_16x16x32_bf16 v[8:11], v[124:127], v[188:191], v[8:11]
	v_mfma_f32_16x16x32_bf16 v[4:7], v[148:151], v[188:191], v[4:7]
	v_mfma_f32_16x16x32_bf16 v[56:59], v[136:139], v[168:171], v[56:59]
	v_mfma_f32_16x16x32_bf16 v[52:55], v[160:163], v[168:171], v[52:55]
	v_mfma_f32_16x16x32_bf16 v[40:43], v[136:139], v[176:179], v[40:43]
	v_mfma_f32_16x16x32_bf16 v[36:39], v[160:163], v[176:179], v[36:39]
	v_mfma_f32_16x16x32_bf16 v[24:27], v[136:139], v[184:187], v[24:27]
	v_mfma_f32_16x16x32_bf16 v[20:23], v[160:163], v[184:187], v[20:23]
	v_mfma_f32_16x16x32_bf16 v[8:11], v[136:139], v[192:195], v[8:11]
	v_mfma_f32_16x16x32_bf16 v[4:7], v[160:163], v[192:195], v[4:7]
	s_setprio 0
	s_barrier
	s_add_u32 s80, s80, 0x100
	s_addc_u32 s81, s81, 0
	s_add_u32 s42, s42, 0x100
	s_addc_u32 s43, s43, 0
	s_cmp_ge_i32 s82, s75
	s_mov_b32 s52, s82
	s_cbranch_scc0 .LBB0_1104
	s_and_b64 vcc, exec, s[38:39]
	s_cbranch_vccz .LBB0_1107
	s_barrier

; #define PG8_STAGE(bufoff, gbase, voff) do { _Pragma("unroll") for (int _i = 0; _i < 2; ++_i) \
;         __builtin_amdgcn_global_load_lds((const unsigned*)((const char*)(gbase) + (voff)[_i]), (LAS unsigned*)(lds + (bufoff) + ldsw + _i * 8192), 16, 0, 0); } while (0)
; #define PG8_LDA(dst, b, h) do { _Pragma("unroll") for (int m = 0; m < 4; ++m) _Pragma("unroll") for (int k = 0; k < 2; ++k) dst[m][k] = *(const LAS bf16x8*)(lds + PG8_SA(b, h) + aoff + m * 2048 + k * 1024); } while (0)
; #define PG8_LDB(dst, b, h) do { _Pragma("unroll") for (int n = 0; n < 2; ++n) _Pragma("unroll") for (int k = 0; k < 2; ++k) dst[n][k] = *(const LAS bf16x8*)(lds + PG8_SB(b, h) + boff + n * 2048 + k * 1024); } while (0)
; #define PG8_MMA(ai, bj, At, Bt) do { __builtin_amdgcn_s_setprio(1); _Pragma("unroll") for (int m = 0; m < 4; ++m) _Pragma("unroll") for (int n = 0; n < 2; ++n) _Pragma("unroll") for (int k = 0; k < 2; ++k) \
;         acc[ai][bj][m][n] = __builtin_amdgcn_mfma_f32_16x16x32_bf16(Bt[n][k], At[m][k], acc[ai][bj][m][n], 0, 0, 0); __builtin_amdgcn_s_setprio(0); } while (0)
; #define PG8_WAIT_V(n) asm volatile("s_waitcnt vmcnt(" #n ")" ::: "memory")
; #define PG8_WAIT_L(n) asm volatile("s_waitcnt lgkmcnt(" #n ")" ::: "memory")
; #define PG8_BAR __builtin_amdgcn_s_barrier()
; template <class Epi, class Sched>
; DI void gemm_phase(LAS unsigned char* lds, const Sched& S, const Epi& E) {
;     ...
;         for (int t = 0; t < nt; t += 2) {
;             const bool last = (t == nt - 2);
;             const char* a1 = cA + (size_t)(t + 1) * kstep;
;             const char* a2 = last ? nA : cA + (size_t)(t + 2) * kstep; const char* b2 = last ? nB : cB + (size_t)(t + 2) * kstep;
;             const char* a3 = a2 + kstep; const char* b3 = b2 + kstep;
;             if constexpr (Epi::HOOK) { if (cur.ks < 0 && (t == 16 || t == 32)) E.hook(acc, cur, t >> 4, wr, wc, fr, fq); }
;             PG8_LDB(B0, 0, 0); PG8_LDB(B1, 0, 1); PG8_SCHED; PG8_LDA(At, 0, 0); PG8_STAGE(PG8_SA(1, 1), a1 + hstepA, voffA);
;             PG8_WAIT_V(8); PG8_WAIT_L(0); PG8_BAR; PG8_MMA(0, 0, At, B0); PG8_MMA(0, 1, At, B1); PG8_BAR; PG8_SCHED;
;             PG8_LDA(At, 0, 1); PG8_STAGE(PG8_SB(0, 0), b2, voffB); PG8_STAGE(PG8_SB(0, 1), b2 + hstepB, voffB); PG8_STAGE(PG8_SA(0, 0), a2, voffA);
;             PG8_WAIT_V(8); PG8_WAIT_L(0); PG8_BAR; PG8_MMA(1, 0, At, B0); PG8_MMA(1, 1, At, B1); PG8_BAR; PG8_SCHED;
.LBB0_1184:
	s_add_i32 s85, s54, 2
	s_add_u32 s55, s42, 0xfff80080
	s_addc_u32 s56, s43, -1
	s_add_i32 s86, 0, 0x10000
	s_cmp_eq_u32 s81, s54
	s_cselect_b32 s57, s58, s56
	s_cselect_b32 s56, s59, s55
	v_add_u32_e32 v149, s86, v146
	s_cselect_b32 s55, s60, s83
	s_cselect_b32 s54, s61, s82
	s_add_i32 s88, 0, 0x14000
	ds_read_b128 v[142:145], v149
	ds_read_b128 v[150:153], v149 offset:1024
	ds_read_b128 v[154:157], v149 offset:2048
	ds_read_b128 v[158:161], v149 offset:3072
	v_add_u32_e32 v149, s88, v146
	ds_read_b128 v[162:165], v149
	ds_read_b128 v[166:169], v149 offset:1024
	ds_read_b128 v[170:173], v149 offset:2048
	ds_read_b128 v[174:177], v149 offset:3072
	s_add_i32 m0, s26, 0xc000
	ds_read_b128 v[178:181], v148
	ds_read_b128 v[182:185], v148 offset:1024
	ds_read_b128 v[186:189], v148 offset:2048
	ds_read_b128 v[190:193], v148 offset:3072
	ds_read_b128 v[204:207], v148 offset:4096
	ds_read_b128 v[208:211], v148 offset:5120
	ds_read_b128 v[212:215], v148 offset:6144
	global_load_lds_dwordx4 v140, s[42:43]
	s_add_i32 m0, s26, 0xe000
	ds_read_b128 v[230:233], v148 offset:7168
	global_load_lds_dwordx4 v138, s[42:43]
	s_waitcnt vmcnt(8)
	s_waitcnt lgkmcnt(0)
	s_barrier
	s_setprio 1
	s_waitcnt lgkmcnt(0)
	v_mfma_f32_16x16x32_bf16 v[128:131], v[142:145], v[178:181], v[128:131]
	v_mfma_f32_16x16x32_bf16 v[124:127], v[154:157], v[178:181], v[124:127]
	v_mfma_f32_16x16x32_bf16 v[112:115], v[142:145], v[186:189], v[112:115]
	v_mfma_f32_16x16x32_bf16 v[108:111], v[154:157], v[186:189], v[108:111]
	v_mfma_f32_16x16x32_bf16 v[96:99], v[142:145], v[204:207], v[96:99]
	v_mfma_f32_16x16x32_bf16 v[92:95], v[154:157], v[204:207], v[92:95]
	v_mfma_f32_16x16x32_bf16 v[80:83], v[142:145], v[212:215], v[80:83]
	v_mfma_f32_16x16x32_bf16 v[76:79], v[154:157], v[212:215], v[76:79]
	v_mfma_f32_16x16x32_bf16 v[128:131], v[150:153], v[182:185], v[128:131]
	v_mfma_f32_16x16x32_bf16 v[124:127], v[158:161], v[182:185], v[124:127]
	v_mfma_f32_16x16x32_bf16 v[112:115], v[150:153], v[190:193], v[112:115]
	v_mfma_f32_16x16x32_bf16 v[108:111], v[158:161], v[190:193], v[108:111]
	v_mfma_f32_16x16x32_bf16 v[96:99], v[150:153], v[208:211], v[96:99]
	v_mfma_f32_16x16x32_bf16 v[92:95], v[158:161], v[208:211], v[92:95]
	v_mfma_f32_16x16x32_bf16 v[80:83], v[150:153], v[230:233], v[80:83]
	v_mfma_f32_16x16x32_bf16 v[76:79], v[158:161], v[230:233], v[76:79]
	s_setprio 0
	s_setprio 1
	v_mfma_f32_16x16x32_bf16 v[120:123], v[162:165], v[178:181], v[120:123]
	v_mfma_f32_16x16x32_bf16 v[116:119], v[170:173], v[178:181], v[116:119]
	v_mfma_f32_16x16x32_bf16 v[104:107], v[162:165], v[186:189], v[104:107]
	v_mfma_f32_16x16x32_bf16 v[100:103], v[170:173], v[186:189], v[100:103]
	v_mfma_f32_16x16x32_bf16 v[88:91], v[162:165], v[204:207], v[88:91]
	v_mfma_f32_16x16x32_bf16 v[84:87], v[170:173], v[204:207], v[84:87]
	v_mfma_f32_16x16x32_bf16 v[72:75], v[162:165], v[212:215], v[72:75]
	v_mfma_f32_16x16x32_bf16 v[68:71], v[170:173], v[212:215], v[68:71]
	v_mfma_f32_16x16x32_bf16 v[120:123], v[166:169], v[182:185], v[120:123]
	v_mfma_f32_16x16x32_bf16 v[116:119], v[174:177], v[182:185], v[116:119]
	v_mfma_f32_16x16x32_bf16 v[104:107], v[166:169], v[190:193], v[104:107]
	v_mfma_f32_16x16x32_bf16 v[100:103], v[174:177], v[190:193], v[100:103]
	v_mfma_f32_16x16x32_bf16 v[88:91], v[166:169], v[208:211], v[88:91]
	v_mfma_f32_16x16x32_bf16 v[84:87], v[174:177], v[208:211], v[84:87]
	v_mfma_f32_16x16x32_bf16 v[72:75], v[166:169], v[230:233], v[72:75]
	v_mfma_f32_16x16x32_bf16 v[68:71], v[174:177], v[230:233], v[68:71]
	s_setprio 0
	s_barrier
	s_add_i32 s86, s86, s23
	s_mov_b32 m0, s86
	ds_read_b128 v[178:181], v148 offset:16384
	ds_read_b128 v[182:185], v148 offset:17408
	ds_read_b128 v[186:189], v148 offset:18432
	ds_read_b128 v[190:193], v148 offset:19456
	global_load_lds_dwordx4 v2, s[54:55]
	s_add_i32 m0, s86, 0x2000
	s_add_u32 s86, s54, 0x80000
	s_addc_u32 s87, s55, 0
	s_add_i32 s88, s88, s23
	global_load_lds_dwordx4 v136, s[54:55]
	s_mov_b32 m0, s88
	ds_read_b128 v[230:233], v148 offset:23552
	global_load_lds_dwordx4 v2, s[86:87]
	s_add_i32 m0, s88, 0x2000
	ds_read_b128 v[212:215], v148 offset:22528
	global_load_lds_dwordx4 v136, s[86:87]
	s_add_u32 s98, s56, 0x80
	s_addc_u32 s99, s57, 0
	s_mov_b32 m0, s26
	ds_read_b128 v[208:211], v148 offset:21504
	global_load_lds_dwordx4 v132, s[56:57]
	s_mov_b32 m0, s27
	ds_read_b128 v[204:207], v148 offset:20480
	global_load_lds_dwordx4 v134, s[56:57]
	s_waitcnt vmcnt(8)
	s_waitcnt lgkmcnt(0)
	s_barrier
	s_setprio 1
	s_waitcnt lgkmcnt(0)
	v_mfma_f32_16x16x32_bf16 v[64:67], v[142:145], v[178:181], v[64:67]
	v_mfma_f32_16x16x32_bf16 v[60:63], v[154:157], v[178:181], v[60:63]
	v_mfma_f32_16x16x32_bf16 v[48:51], v[142:145], v[186:189], v[48:51]
	v_mfma_f32_16x16x32_bf16 v[44:47], v[154:157], v[186:189], v[44:47]
	v_mfma_f32_16x16x32_bf16 v[32:35], v[142:145], v[204:207], v[32:35]
	v_mfma_f32_16x16x32_bf16 v[28:31], v[154:157], v[204:207], v[28:31]
	v_mfma_f32_16x16x32_bf16 v[16:19], v[142:145], v[212:215], v[16:19]
	v_mfma_f32_16x16x32_bf16 v[12:15], v[154:157], v[212:215], v[12:15]
	v_mfma_f32_16x16x32_bf16 v[64:67], v[150:153], v[182:185], v[64:67]
	v_mfma_f32_16x16x32_bf16 v[60:63], v[158:161], v[182:185], v[60:63]
	v_mfma_f32_16x16x32_bf16 v[48:51], v[150:153], v[190:193], v[48:51]
	v_mfma_f32_16x16x32_bf16 v[44:47], v[158:161], v[190:193], v[44:47]
	v_mfma_f32_16x16x32_bf16 v[32:35], v[150:153], v[208:211], v[32:35]
	v_mfma_f32_16x16x32_bf16 v[28:31], v[158:161], v[208:211], v[28:31]
	v_mfma_f32_16x16x32_bf16 v[16:19], v[150:153], v[230:233], v[16:19]
	v_mfma_f32_16x16x32_bf16 v[12:15], v[158:161], v[230:233], v[12:15]
	s_setprio 0
	s_setprio 1
	v_mfma_f32_16x16x32_bf16 v[56:59], v[162:165], v[178:181], v[56:59]
	v_mfma_f32_16x16x32_bf16 v[52:55], v[170:173], v[178:181], v[52:55]
	v_mfma_f32_16x16x32_bf16 v[40:43], v[162:165], v[186:189], v[40:43]
	v_mfma_f32_16x16x32_bf16 v[36:39], v[170:173], v[186:189], v[36:39]
	v_mfma_f32_16x16x32_bf16 v[24:27], v[162:165], v[204:207], v[24:27]
	v_mfma_f32_16x16x32_bf16 v[20:23], v[170:173], v[204:207], v[20:23]
	v_mfma_f32_16x16x32_bf16 v[8:11], v[162:165], v[212:215], v[8:11]
	v_mfma_f32_16x16x32_bf16 v[4:7], v[170:173], v[212:215], v[4:7]
	v_mfma_f32_16x16x32_bf16 v[56:59], v[166:169], v[182:185], v[56:59]
	v_mfma_f32_16x16x32_bf16 v[52:55], v[174:177], v[182:185], v[52:55]
	v_mfma_f32_16x16x32_bf16 v[40:43], v[166:169], v[190:193], v[40:43]
	v_mfma_f32_16x16x32_bf16 v[36:39], v[174:177], v[190:193], v[36:39]
	v_mfma_f32_16x16x32_bf16 v[24:27], v[166:169], v[208:211], v[24:27]
	v_mfma_f32_16x16x32_bf16 v[20:23], v[174:177], v[208:211], v[20:23]
	v_mfma_f32_16x16x32_bf16 v[8:11], v[166:169], v[230:233], v[8:11]
	v_mfma_f32_16x16x32_bf16 v[4:7], v[174:177], v[230:233], v[4:7]
	s_setprio 0
	s_barrier
; #define PG8_STAGE(bufoff, gbase, voff) do { _Pragma("unroll") for (int _i = 0; _i < 2; ++_i) \
;         __builtin_amdgcn_global_load_lds((const unsigned*)((const char*)(gbase) + (voff)[_i]), (LAS unsigned*)(lds + (bufoff) + ldsw + _i * 8192), 16, 0, 0); } while (0)
; #define PG8_LDA(dst, b, h) do { _Pragma("unroll") for (int m = 0; m < 4; ++m) _Pragma("unroll") for (int k = 0; k < 2; ++k) dst[m][k] = *(const LAS bf16x8*)(lds + PG8_SA(b, h) + aoff + m * 2048 + k * 1024); } while (0)
; #define PG8_LDB(dst, b, h) do { _Pragma("unroll") for (int n = 0; n < 2; ++n) _Pragma("unroll") for (int k = 0; k < 2; ++k) dst[n][k] = *(const LAS bf16x8*)(lds + PG8_SB(b, h) + boff + n * 2048 + k * 1024); } while (0)
; #define PG8_MMA(ai, bj, At, Bt) do { __builtin_amdgcn_s_setprio(1); _Pragma("unroll") for (int m = 0; m < 4; ++m) _Pragma("unroll") for (int n = 0; n < 2; ++n) _Pragma("unroll") for (int k = 0; k < 2; ++k) \
;         acc[ai][bj][m][n] = __builtin_amdgcn_mfma_f32_16x16x32_bf16(Bt[n][k], At[m][k], acc[ai][bj][m][n], 0, 0, 0); __builtin_amdgcn_s_setprio(0); } while (0)
; #define PG8_WAIT_V(n) asm volatile("s_waitcnt vmcnt(" #n ")" ::: "memory")
; #define PG8_WAIT_L(n) asm volatile("s_waitcnt lgkmcnt(" #n ")" ::: "memory")
; #define PG8_BAR __builtin_amdgcn_s_barrier()
; #define PG8_SCHED __builtin_amdgcn_sched_barrier(0)
; template <class Epi, class Sched>
; DI void gemm_phase(LAS unsigned char* lds, const Sched& S, const Epi& E) {
;     ...
;             PG8_LDB(B0, 1, 0); PG8_LDB(B1, 1, 1); PG8_SCHED; PG8_LDA(At, 1, 0); PG8_STAGE(PG8_SA(0, 1), a2 + hstepA, voffA);
;             PG8_WAIT_V(8); PG8_WAIT_L(0); PG8_BAR; PG8_MMA(0, 0, At, B0); PG8_MMA(0, 1, At, B1); PG8_BAR; PG8_SCHED;
;             PG8_LDA(At, 1, 1); PG8_STAGE(PG8_SB(1, 0), b3, voffB); PG8_STAGE(PG8_SB(1, 1), b3 + hstepB, voffB); PG8_STAGE(PG8_SA(1, 0), a3, voffA);
;             PG8_WAIT_V(8); PG8_WAIT_L(0); PG8_BAR; PG8_MMA(1, 0, At, B0); PG8_MMA(1, 1, At, B1); PG8_BAR; PG8_SCHED;
;         }
;         if (wr == 0) PG8_BAR;
	s_add_i32 s86, 0, 0x18000
	v_add_u32_e32 v149, s86, v146
	s_add_i32 s87, 0, 0x1c000
	ds_read_b128 v[142:145], v149
	ds_read_b128 v[150:153], v149 offset:1024
	ds_read_b128 v[154:157], v149 offset:2048
	ds_read_b128 v[158:161], v149 offset:3072
	v_add_u32_e32 v149, s87, v146
	ds_read_b128 v[162:165], v149
	ds_read_b128 v[166:169], v149 offset:1024
	ds_read_b128 v[170:173], v149 offset:2048
	ds_read_b128 v[174:177], v149 offset:3072
	s_add_u32 s56, s56, 0x80000
	s_addc_u32 s57, s57, 0
	s_mov_b32 m0, s65
	ds_read_b128 v[178:181], v148 offset:32768
	ds_read_b128 v[182:185], v148 offset:33792
	ds_read_b128 v[186:189], v148 offset:34816
	ds_read_b128 v[190:193], v148 offset:35840
	ds_read_b128 v[204:207], v148 offset:36864
	ds_read_b128 v[208:211], v148 offset:37888
	ds_read_b128 v[212:215], v148 offset:38912
	global_load_lds_dwordx4 v132, s[56:57]
	s_mov_b32 m0, s66
	ds_read_b128 v[230:233], v148 offset:39936
	global_load_lds_dwordx4 v134, s[56:57]
	s_waitcnt vmcnt(8)
	s_waitcnt lgkmcnt(0)
	s_barrier
	s_setprio 1
	s_waitcnt lgkmcnt(0)
	v_mfma_f32_16x16x32_bf16 v[128:131], v[142:145], v[178:181], v[128:131]
	v_mfma_f32_16x16x32_bf16 v[124:127], v[154:157], v[178:181], v[124:127]
	v_mfma_f32_16x16x32_bf16 v[112:115], v[142:145], v[186:189], v[112:115]
	v_mfma_f32_16x16x32_bf16 v[108:111], v[154:157], v[186:189], v[108:111]
	v_mfma_f32_16x16x32_bf16 v[96:99], v[142:145], v[204:207], v[96:99]
	v_mfma_f32_16x16x32_bf16 v[92:95], v[154:157], v[204:207], v[92:95]
	v_mfma_f32_16x16x32_bf16 v[80:83], v[142:145], v[212:215], v[80:83]
	v_mfma_f32_16x16x32_bf16 v[76:79], v[154:157], v[212:215], v[76:79]
	v_mfma_f32_16x16x32_bf16 v[128:131], v[150:153], v[182:185], v[128:131]
	v_mfma_f32_16x16x32_bf16 v[124:127], v[158:161], v[182:185], v[124:127]
	v_mfma_f32_16x16x32_bf16 v[112:115], v[150:153], v[190:193], v[112:115]
	v_mfma_f32_16x16x32_bf16 v[108:111], v[158:161], v[190:193], v[108:111]
	v_mfma_f32_16x16x32_bf16 v[96:99], v[150:153], v[208:211], v[96:99]
	v_mfma_f32_16x16x32_bf16 v[92:95], v[158:161], v[208:211], v[92:95]
	v_mfma_f32_16x16x32_bf16 v[80:83], v[150:153], v[230:233], v[80:83]
	v_mfma_f32_16x16x32_bf16 v[76:79], v[158:161], v[230:233], v[76:79]
	s_setprio 0
	s_setprio 1
	v_mfma_f32_16x16x32_bf16 v[120:123], v[162:165], v[178:181], v[120:123]
	v_mfma_f32_16x16x32_bf16 v[116:119], v[170:173], v[178:181], v[116:119]
	v_mfma_f32_16x16x32_bf16 v[104:107], v[162:165], v[186:189], v[104:107]
	v_mfma_f32_16x16x32_bf16 v[100:103], v[170:173], v[186:189], v[100:103]
	v_mfma_f32_16x16x32_bf16 v[88:91], v[162:165], v[204:207], v[88:91]
	v_mfma_f32_16x16x32_bf16 v[84:87], v[170:173], v[204:207], v[84:87]
	v_mfma_f32_16x16x32_bf16 v[72:75], v[162:165], v[212:215], v[72:75]
	v_mfma_f32_16x16x32_bf16 v[68:71], v[170:173], v[212:215], v[68:71]
	v_mfma_f32_16x16x32_bf16 v[120:123], v[166:169], v[182:185], v[120:123]
	v_mfma_f32_16x16x32_bf16 v[116:119], v[174:177], v[182:185], v[116:119]
	v_mfma_f32_16x16x32_bf16 v[104:107], v[166:169], v[190:193], v[104:107]
	v_mfma_f32_16x16x32_bf16 v[100:103], v[174:177], v[190:193], v[100:103]
	v_mfma_f32_16x16x32_bf16 v[88:91], v[166:169], v[208:211], v[88:91]
	v_mfma_f32_16x16x32_bf16 v[84:87], v[174:177], v[208:211], v[84:87]
	v_mfma_f32_16x16x32_bf16 v[72:75], v[166:169], v[230:233], v[72:75]
	v_mfma_f32_16x16x32_bf16 v[68:71], v[174:177], v[230:233], v[68:71]
	s_setprio 0
	s_barrier
	s_add_i32 s56, s86, s23
	s_add_u32 s54, s54, 0x80
	s_addc_u32 s55, s55, 0
	s_mov_b32 m0, s56
	ds_read_b128 v[178:181], v148 offset:49152
	ds_read_b128 v[182:185], v148 offset:50176
	ds_read_b128 v[186:189], v148 offset:51200
	ds_read_b128 v[190:193], v148 offset:52224
	global_load_lds_dwordx4 v2, s[54:55]
	s_add_i32 m0, s56, 0x2000
	s_add_i32 s56, s87, s23
	global_load_lds_dwordx4 v136, s[54:55]
	s_add_u32 s54, s54, 0x80000
	s_addc_u32 s55, s55, 0
	s_mov_b32 m0, s56
	ds_read_b128 v[230:233], v148 offset:56320
	global_load_lds_dwordx4 v2, s[54:55]
	s_add_i32 m0, s56, 0x2000
	ds_read_b128 v[212:215], v148 offset:55296
	global_load_lds_dwordx4 v136, s[54:55]
	s_mov_b32 m0, s73
	ds_read_b128 v[208:211], v148 offset:54272
	global_load_lds_dwordx4 v132, s[98:99]
	s_mov_b32 m0, s74
	ds_read_b128 v[204:207], v148 offset:53248
	global_load_lds_dwordx4 v134, s[98:99]
	s_waitcnt vmcnt(8)
	s_waitcnt lgkmcnt(0)
	s_barrier
	s_setprio 1
	s_waitcnt lgkmcnt(0)
	v_mfma_f32_16x16x32_bf16 v[64:67], v[142:145], v[178:181], v[64:67]
	v_mfma_f32_16x16x32_bf16 v[60:63], v[154:157], v[178:181], v[60:63]
	v_mfma_f32_16x16x32_bf16 v[48:51], v[142:145], v[186:189], v[48:51]
	v_mfma_f32_16x16x32_bf16 v[44:47], v[154:157], v[186:189], v[44:47]
	v_mfma_f32_16x16x32_bf16 v[32:35], v[142:145], v[204:207], v[32:35]
	v_mfma_f32_16x16x32_bf16 v[28:31], v[154:157], v[204:207], v[28:31]
	v_mfma_f32_16x16x32_bf16 v[16:19], v[142:145], v[212:215], v[16:19]
	v_mfma_f32_16x16x32_bf16 v[12:15], v[154:157], v[212:215], v[12:15]
	v_mfma_f32_16x16x32_bf16 v[64:67], v[150:153], v[182:185], v[64:67]
	v_mfma_f32_16x16x32_bf16 v[60:63], v[158:161], v[182:185], v[60:63]
	v_mfma_f32_16x16x32_bf16 v[48:51], v[150:153], v[190:193], v[48:51]
	v_mfma_f32_16x16x32_bf16 v[44:47], v[158:161], v[190:193], v[44:47]
	v_mfma_f32_16x16x32_bf16 v[32:35], v[150:153], v[208:211], v[32:35]
	v_mfma_f32_16x16x32_bf16 v[28:31], v[158:161], v[208:211], v[28:31]
	v_mfma_f32_16x16x32_bf16 v[16:19], v[150:153], v[230:233], v[16:19]
	v_mfma_f32_16x16x32_bf16 v[12:15], v[158:161], v[230:233], v[12:15]
	s_setprio 0
	s_setprio 1
	v_mfma_f32_16x16x32_bf16 v[56:59], v[162:165], v[178:181], v[56:59]
	v_mfma_f32_16x16x32_bf16 v[52:55], v[170:173], v[178:181], v[52:55]
	v_mfma_f32_16x16x32_bf16 v[40:43], v[162:165], v[186:189], v[40:43]
	v_mfma_f32_16x16x32_bf16 v[36:39], v[170:173], v[186:189], v[36:39]
	v_mfma_f32_16x16x32_bf16 v[24:27], v[162:165], v[204:207], v[24:27]
	v_mfma_f32_16x16x32_bf16 v[20:23], v[170:173], v[204:207], v[20:23]
	v_mfma_f32_16x16x32_bf16 v[8:11], v[162:165], v[212:215], v[8:11]
	v_mfma_f32_16x16x32_bf16 v[4:7], v[170:173], v[212:215], v[4:7]
	v_mfma_f32_16x16x32_bf16 v[56:59], v[166:169], v[182:185], v[56:59]
	v_mfma_f32_16x16x32_bf16 v[52:55], v[174:177], v[182:185], v[52:55]
	v_mfma_f32_16x16x32_bf16 v[40:43], v[166:169], v[190:193], v[40:43]
	v_mfma_f32_16x16x32_bf16 v[36:39], v[174:177], v[190:193], v[36:39]
	v_mfma_f32_16x16x32_bf16 v[24:27], v[166:169], v[208:211], v[24:27]
	v_mfma_f32_16x16x32_bf16 v[20:23], v[174:177], v[208:211], v[20:23]
	v_mfma_f32_16x16x32_bf16 v[8:11], v[166:169], v[230:233], v[8:11]
	v_mfma_f32_16x16x32_bf16 v[4:7], v[174:177], v[230:233], v[4:7]
	s_setprio 0
	s_barrier
	s_add_u32 s82, s82, 0x100
	s_addc_u32 s83, s83, 0
	s_add_u32 s42, s42, 0x100
	s_addc_u32 s43, s43, 0
	s_cmp_ge_i32 s85, s79
	s_mov_b32 s54, s85
	s_cbranch_scc0 .LBB0_1184
	s_and_b64 vcc, exec, s[8:9]
	s_cbranch_vccz .LBB0_1187
	s_barrier

; #define PG8_STAGE(bufoff, gbase, voff) do { _Pragma("unroll") for (int _i = 0; _i < 2; ++_i) \
;         __builtin_amdgcn_global_load_lds((const unsigned*)((const char*)(gbase) + (voff)[_i]), (LAS unsigned*)(lds + (bufoff) + ldsw + _i * 8192), 16, 0, 0); } while (0)
; #define PG8_LDA(dst, b, h) do { _Pragma("unroll") for (int m = 0; m < 4; ++m) _Pragma("unroll") for (int k = 0; k < 2; ++k) dst[m][k] = *(const LAS bf16x8*)(lds + PG8_SA(b, h) + aoff + m * 2048 + k * 1024); } while (0)
; #define PG8_LDB(dst, b, h) do { _Pragma("unroll") for (int n = 0; n < 2; ++n) _Pragma("unroll") for (int k = 0; k < 2; ++k) dst[n][k] = *(const LAS bf16x8*)(lds + PG8_SB(b, h) + boff + n * 2048 + k * 1024); } while (0)
; #define PG8_MMA(ai, bj, At, Bt) do { __builtin_amdgcn_s_setprio(1); _Pragma("unroll") for (int m = 0; m < 4; ++m) _Pragma("unroll") for (int n = 0; n < 2; ++n) _Pragma("unroll") for (int k = 0; k < 2; ++k) \
;         acc[ai][bj][m][n] = __builtin_amdgcn_mfma_f32_16x16x32_bf16(Bt[n][k], At[m][k], acc[ai][bj][m][n], 0, 0, 0); __builtin_amdgcn_s_setprio(0); } while (0)
; #define PG8_WAIT_V(n) asm volatile("s_waitcnt vmcnt(" #n ")" ::: "memory")
; #define PG8_WAIT_L(n) asm volatile("s_waitcnt lgkmcnt(" #n ")" ::: "memory")
; #define PG8_BAR __builtin_amdgcn_s_barrier()
; template <class Epi, class Sched>
; DI void gemm_phase(LAS unsigned char* lds, const Sched& S, const Epi& E) {
;     ...
;         for (int t = 0; t < nt; t += 2) {
;             const bool last = (t == nt - 2);
;             const char* a1 = cA + (size_t)(t + 1) * kstep;
;             const char* a2 = last ? nA : cA + (size_t)(t + 2) * kstep; const char* b2 = last ? nB : cB + (size_t)(t + 2) * kstep;
;             const char* a3 = a2 + kstep; const char* b3 = b2 + kstep;
;             if constexpr (Epi::HOOK) { if (cur.ks < 0 && (t == 16 || t == 32)) E.hook(acc, cur, t >> 4, wr, wc, fr, fq); }
;             PG8_LDB(B0, 0, 0); PG8_LDB(B1, 0, 1); PG8_SCHED; PG8_LDA(At, 0, 0); PG8_STAGE(PG8_SA(1, 1), a1 + hstepA, voffA);
;             PG8_WAIT_V(8); PG8_WAIT_L(0); PG8_BAR; PG8_MMA(0, 0, At, B0); PG8_MMA(0, 1, At, B1); PG8_BAR; PG8_SCHED;
;             PG8_LDA(At, 0, 1); PG8_STAGE(PG8_SB(0, 0), b2, voffB); PG8_STAGE(PG8_SB(0, 1), b2 + hstepB, voffB); PG8_STAGE(PG8_SA(0, 0), a2, voffA);
;             PG8_WAIT_V(8); PG8_WAIT_L(0); PG8_BAR; PG8_MMA(1, 0, At, B0); PG8_MMA(1, 1, At, B1); PG8_BAR; PG8_SCHED;
.LBB0_1390:
	s_add_u32 s50, s48, 0xfff80080
	s_addc_u32 s51, s49, -1
	s_add_i32 s66, 0, 0x10000
	s_cmp_eq_u32 s65, 28
	s_cselect_b32 s53, s45, s51
	s_cselect_b32 s52, s44, s50
	s_cselect_b32 s51, s47, s43
	s_cselect_b32 s50, s46, s39
	s_add_i32 s71, 0, 0x14000
	v_add_u32_e32 v160, s66, v148
	v_add_u32_e32 v176, s71, v148
	ds_read_b128 v[144:147], v160
	ds_read_b128 v[152:155], v160 offset:1024
	ds_read_b128 v[156:159], v160 offset:2048
	ds_read_b128 v[160:163], v160 offset:3072
	ds_read_b128 v[164:167], v176
	ds_read_b128 v[168:171], v176 offset:1024
	ds_read_b128 v[172:175], v176 offset:2048
	ds_read_b128 v[176:179], v176 offset:3072
	s_add_i32 m0, s54, 0xc000
	ds_read_b128 v[180:183], v151
	ds_read_b128 v[184:187], v151 offset:1024
	ds_read_b128 v[188:191], v151 offset:2048
	ds_read_b128 v[192:195], v151 offset:3072
	ds_read_b128 v[204:207], v151 offset:4096
	ds_read_b128 v[208:211], v151 offset:5120
	ds_read_b128 v[212:215], v151 offset:6144
	global_load_lds_dwordx4 v142, s[48:49]
	s_add_i32 m0, s54, 0xe000
	ds_read_b128 v[230:233], v151 offset:7168
	global_load_lds_dwordx4 v140, s[48:49]
	s_waitcnt vmcnt(8)
	s_waitcnt lgkmcnt(0)
	s_barrier
	s_setprio 1
	s_waitcnt lgkmcnt(0)
	v_mfma_f32_16x16x32_bf16 v[128:131], v[144:147], v[180:183], v[128:131]
	v_mfma_f32_16x16x32_bf16 v[124:127], v[156:159], v[180:183], v[124:127]
	v_mfma_f32_16x16x32_bf16 v[112:115], v[144:147], v[188:191], v[112:115]
	v_mfma_f32_16x16x32_bf16 v[108:111], v[156:159], v[188:191], v[108:111]
	v_mfma_f32_16x16x32_bf16 v[96:99], v[144:147], v[204:207], v[96:99]
	v_mfma_f32_16x16x32_bf16 v[92:95], v[156:159], v[204:207], v[92:95]
	v_mfma_f32_16x16x32_bf16 v[80:83], v[144:147], v[212:215], v[80:83]
	v_mfma_f32_16x16x32_bf16 v[76:79], v[156:159], v[212:215], v[76:79]
	v_mfma_f32_16x16x32_bf16 v[128:131], v[152:155], v[184:187], v[128:131]
	v_mfma_f32_16x16x32_bf16 v[124:127], v[160:163], v[184:187], v[124:127]
	v_mfma_f32_16x16x32_bf16 v[112:115], v[152:155], v[192:195], v[112:115]
	v_mfma_f32_16x16x32_bf16 v[108:111], v[160:163], v[192:195], v[108:111]
	v_mfma_f32_16x16x32_bf16 v[96:99], v[152:155], v[208:211], v[96:99]
	v_mfma_f32_16x16x32_bf16 v[92:95], v[160:163], v[208:211], v[92:95]
	v_mfma_f32_16x16x32_bf16 v[80:83], v[152:155], v[230:233], v[80:83]
	v_mfma_f32_16x16x32_bf16 v[76:79], v[160:163], v[230:233], v[76:79]
	s_setprio 0
	s_setprio 1
	v_mfma_f32_16x16x32_bf16 v[120:123], v[164:167], v[180:183], v[120:123]
	v_mfma_f32_16x16x32_bf16 v[116:119], v[172:175], v[180:183], v[116:119]
	v_mfma_f32_16x16x32_bf16 v[104:107], v[164:167], v[188:191], v[104:107]
	v_mfma_f32_16x16x32_bf16 v[100:103], v[172:175], v[188:191], v[100:103]
	v_mfma_f32_16x16x32_bf16 v[88:91], v[164:167], v[204:207], v[88:91]
	v_mfma_f32_16x16x32_bf16 v[84:87], v[172:175], v[204:207], v[84:87]
	v_mfma_f32_16x16x32_bf16 v[72:75], v[164:167], v[212:215], v[72:75]
	v_mfma_f32_16x16x32_bf16 v[68:71], v[172:175], v[212:215], v[68:71]
	v_mfma_f32_16x16x32_bf16 v[120:123], v[168:171], v[184:187], v[120:123]
	v_mfma_f32_16x16x32_bf16 v[116:119], v[176:179], v[184:187], v[116:119]
	v_mfma_f32_16x16x32_bf16 v[104:107], v[168:171], v[192:195], v[104:107]
	v_mfma_f32_16x16x32_bf16 v[100:103], v[176:179], v[192:195], v[100:103]
	v_mfma_f32_16x16x32_bf16 v[88:91], v[168:171], v[208:211], v[88:91]
	v_mfma_f32_16x16x32_bf16 v[84:87], v[176:179], v[208:211], v[84:87]
	v_mfma_f32_16x16x32_bf16 v[72:75], v[168:171], v[230:233], v[72:75]
	v_mfma_f32_16x16x32_bf16 v[68:71], v[176:179], v[230:233], v[68:71]
	s_setprio 0
	s_barrier
	s_add_i32 s66, s66, s27
	s_mov_b32 m0, s66
	ds_read_b128 v[180:183], v151 offset:16384
	ds_read_b128 v[184:187], v151 offset:17408
	ds_read_b128 v[188:191], v151 offset:18432
	ds_read_b128 v[192:195], v151 offset:19456
	ds_read_b128 v[204:207], v151 offset:20480
	global_load_lds_dwordx4 v2, s[50:51]
	s_add_i32 m0, s66, 0x2000
	s_add_u32 s66, s50, 0x80000
	s_addc_u32 s67, s51, 0
	s_add_i32 s71, s71, s27
	global_load_lds_dwordx4 v136, s[50:51]
	s_mov_b32 m0, s71
	s_add_u32 s86, s52, 0x80
	s_addc_u32 s87, s53, 0
	global_load_lds_dwordx4 v2, s[66:67]
	s_add_i32 m0, s71, 0x2000
	ds_read_b128 v[230:233], v151 offset:23552
	global_load_lds_dwordx4 v136, s[66:67]
	s_mov_b32 m0, s54
	ds_read_b128 v[212:215], v151 offset:22528
	global_load_lds_dwordx4 v132, s[52:53]
	s_mov_b32 m0, s55
	ds_read_b128 v[208:211], v151 offset:21504
	global_load_lds_dwordx4 v134, s[52:53]
	s_waitcnt vmcnt(8)
	s_waitcnt lgkmcnt(0)
	s_barrier
	s_setprio 1
	s_waitcnt lgkmcnt(0)
	v_mfma_f32_16x16x32_bf16 v[64:67], v[144:147], v[180:183], v[64:67]
	v_mfma_f32_16x16x32_bf16 v[60:63], v[156:159], v[180:183], v[60:63]
	v_mfma_f32_16x16x32_bf16 v[48:51], v[144:147], v[188:191], v[48:51]
	v_mfma_f32_16x16x32_bf16 v[44:47], v[156:159], v[188:191], v[44:47]
	v_mfma_f32_16x16x32_bf16 v[32:35], v[144:147], v[204:207], v[32:35]
	v_mfma_f32_16x16x32_bf16 v[28:31], v[156:159], v[204:207], v[28:31]
	v_mfma_f32_16x16x32_bf16 v[16:19], v[144:147], v[212:215], v[16:19]
	v_mfma_f32_16x16x32_bf16 v[12:15], v[156:159], v[212:215], v[12:15]
	v_mfma_f32_16x16x32_bf16 v[64:67], v[152:155], v[184:187], v[64:67]
	v_mfma_f32_16x16x32_bf16 v[60:63], v[160:163], v[184:187], v[60:63]
	v_mfma_f32_16x16x32_bf16 v[48:51], v[152:155], v[192:195], v[48:51]
	v_mfma_f32_16x16x32_bf16 v[44:47], v[160:163], v[192:195], v[44:47]
	v_mfma_f32_16x16x32_bf16 v[32:35], v[152:155], v[208:211], v[32:35]
	v_mfma_f32_16x16x32_bf16 v[28:31], v[160:163], v[208:211], v[28:31]
	v_mfma_f32_16x16x32_bf16 v[16:19], v[152:155], v[230:233], v[16:19]
	v_mfma_f32_16x16x32_bf16 v[12:15], v[160:163], v[230:233], v[12:15]
	s_setprio 0
	s_setprio 1
	v_mfma_f32_16x16x32_bf16 v[56:59], v[164:167], v[180:183], v[56:59]
	v_mfma_f32_16x16x32_bf16 v[52:55], v[172:175], v[180:183], v[52:55]
	v_mfma_f32_16x16x32_bf16 v[40:43], v[164:167], v[188:191], v[40:43]
	v_mfma_f32_16x16x32_bf16 v[36:39], v[172:175], v[188:191], v[36:39]
	v_mfma_f32_16x16x32_bf16 v[24:27], v[164:167], v[204:207], v[24:27]
	v_mfma_f32_16x16x32_bf16 v[20:23], v[172:175], v[204:207], v[20:23]
	v_mfma_f32_16x16x32_bf16 v[8:11], v[164:167], v[212:215], v[8:11]
	v_mfma_f32_16x16x32_bf16 v[4:7], v[172:175], v[212:215], v[4:7]
	v_mfma_f32_16x16x32_bf16 v[56:59], v[168:171], v[184:187], v[56:59]
	v_mfma_f32_16x16x32_bf16 v[52:55], v[176:179], v[184:187], v[52:55]
	v_mfma_f32_16x16x32_bf16 v[40:43], v[168:171], v[192:195], v[40:43]
	v_mfma_f32_16x16x32_bf16 v[36:39], v[176:179], v[192:195], v[36:39]
	v_mfma_f32_16x16x32_bf16 v[24:27], v[168:171], v[208:211], v[24:27]
	v_mfma_f32_16x16x32_bf16 v[20:23], v[176:179], v[208:211], v[20:23]
	v_mfma_f32_16x16x32_bf16 v[8:11], v[168:171], v[230:233], v[8:11]
	v_mfma_f32_16x16x32_bf16 v[4:7], v[176:179], v[230:233], v[4:7]
	s_setprio 0
	s_barrier
; #define PG8_STAGE(bufoff, gbase, voff) do { _Pragma("unroll") for (int _i = 0; _i < 2; ++_i) \
;         __builtin_amdgcn_global_load_lds((const unsigned*)((const char*)(gbase) + (voff)[_i]), (LAS unsigned*)(lds + (bufoff) + ldsw + _i * 8192), 16, 0, 0); } while (0)
; #define PG8_LDA(dst, b, h) do { _Pragma("unroll") for (int m = 0; m < 4; ++m) _Pragma("unroll") for (int k = 0; k < 2; ++k) dst[m][k] = *(const LAS bf16x8*)(lds + PG8_SA(b, h) + aoff + m * 2048 + k * 1024); } while (0)
; #define PG8_LDB(dst, b, h) do { _Pragma("unroll") for (int n = 0; n < 2; ++n) _Pragma("unroll") for (int k = 0; k < 2; ++k) dst[n][k] = *(const LAS bf16x8*)(lds + PG8_SB(b, h) + boff + n * 2048 + k * 1024); } while (0)
; #define PG8_MMA(ai, bj, At, Bt) do { __builtin_amdgcn_s_setprio(1); _Pragma("unroll") for (int m = 0; m < 4; ++m) _Pragma("unroll") for (int n = 0; n < 2; ++n) _Pragma("unroll") for (int k = 0; k < 2; ++k) \
;         acc[ai][bj][m][n] = __builtin_amdgcn_mfma_f32_16x16x32_bf16(Bt[n][k], At[m][k], acc[ai][bj][m][n], 0, 0, 0); __builtin_amdgcn_s_setprio(0); } while (0)
; #define PG8_WAIT_V(n) asm volatile("s_waitcnt vmcnt(" #n ")" ::: "memory")
; #define PG8_WAIT_L(n) asm volatile("s_waitcnt lgkmcnt(" #n ")" ::: "memory")
; #define PG8_BAR __builtin_amdgcn_s_barrier()
; #define PG8_SCHED __builtin_amdgcn_sched_barrier(0)
; template <class Epi, class Sched>
; DI void gemm_phase(LAS unsigned char* lds, const Sched& S, const Epi& E) {
;     ...
;             PG8_LDB(B0, 1, 0); PG8_LDB(B1, 1, 1); PG8_SCHED; PG8_LDA(At, 1, 0); PG8_STAGE(PG8_SA(0, 1), a2 + hstepA, voffA);
;             PG8_WAIT_V(8); PG8_WAIT_L(0); PG8_BAR; PG8_MMA(0, 0, At, B0); PG8_MMA(0, 1, At, B1); PG8_BAR; PG8_SCHED;
;             PG8_LDA(At, 1, 1); PG8_STAGE(PG8_SB(1, 0), b3, voffB); PG8_STAGE(PG8_SB(1, 1), b3 + hstepB, voffB); PG8_STAGE(PG8_SA(1, 0), a3, voffA);
;             PG8_WAIT_V(8); PG8_WAIT_L(0); PG8_BAR; PG8_MMA(1, 0, At, B0); PG8_MMA(1, 1, At, B1); PG8_BAR; PG8_SCHED;
;         }
;         if (wr == 0) PG8_BAR;
	s_add_i32 s66, 0, 0x18000
	s_add_i32 s67, 0, 0x1c000
	v_add_u32_e32 v160, s66, v148
	v_add_u32_e32 v176, s67, v148
	ds_read_b128 v[144:147], v160
	ds_read_b128 v[152:155], v160 offset:1024
	ds_read_b128 v[156:159], v160 offset:2048
	ds_read_b128 v[160:163], v160 offset:3072
	ds_read_b128 v[164:167], v176
	ds_read_b128 v[168:171], v176 offset:1024
	ds_read_b128 v[172:175], v176 offset:2048
	ds_read_b128 v[176:179], v176 offset:3072
	s_add_u32 s52, s52, 0x80000
	s_addc_u32 s53, s53, 0
	s_mov_b32 m0, s56
	ds_read_b128 v[180:183], v151 offset:32768
	ds_read_b128 v[184:187], v151 offset:33792
	ds_read_b128 v[188:191], v151 offset:34816
	ds_read_b128 v[192:195], v151 offset:35840
	ds_read_b128 v[204:207], v151 offset:36864
	ds_read_b128 v[208:211], v151 offset:37888
	ds_read_b128 v[212:215], v151 offset:38912
	global_load_lds_dwordx4 v132, s[52:53]
	s_mov_b32 m0, s57
	ds_read_b128 v[230:233], v151 offset:39936
	global_load_lds_dwordx4 v134, s[52:53]
	s_waitcnt vmcnt(8)
	s_waitcnt lgkmcnt(0)
	s_barrier
	s_setprio 1
	s_waitcnt lgkmcnt(0)
	v_mfma_f32_16x16x32_bf16 v[128:131], v[144:147], v[180:183], v[128:131]
	v_mfma_f32_16x16x32_bf16 v[124:127], v[156:159], v[180:183], v[124:127]
	v_mfma_f32_16x16x32_bf16 v[112:115], v[144:147], v[188:191], v[112:115]
	v_mfma_f32_16x16x32_bf16 v[108:111], v[156:159], v[188:191], v[108:111]
	v_mfma_f32_16x16x32_bf16 v[96:99], v[144:147], v[204:207], v[96:99]
	v_mfma_f32_16x16x32_bf16 v[92:95], v[156:159], v[204:207], v[92:95]
	v_mfma_f32_16x16x32_bf16 v[80:83], v[144:147], v[212:215], v[80:83]
	v_mfma_f32_16x16x32_bf16 v[76:79], v[156:159], v[212:215], v[76:79]
	v_mfma_f32_16x16x32_bf16 v[128:131], v[152:155], v[184:187], v[128:131]
	v_mfma_f32_16x16x32_bf16 v[124:127], v[160:163], v[184:187], v[124:127]
	v_mfma_f32_16x16x32_bf16 v[112:115], v[152:155], v[192:195], v[112:115]
	v_mfma_f32_16x16x32_bf16 v[108:111], v[160:163], v[192:195], v[108:111]
	v_mfma_f32_16x16x32_bf16 v[96:99], v[152:155], v[208:211], v[96:99]
	v_mfma_f32_16x16x32_bf16 v[92:95], v[160:163], v[208:211], v[92:95]
	v_mfma_f32_16x16x32_bf16 v[80:83], v[152:155], v[230:233], v[80:83]
	v_mfma_f32_16x16x32_bf16 v[76:79], v[160:163], v[230:233], v[76:79]
	s_setprio 0
	s_setprio 1
	v_mfma_f32_16x16x32_bf16 v[120:123], v[164:167], v[180:183], v[120:123]
	v_mfma_f32_16x16x32_bf16 v[116:119], v[172:175], v[180:183], v[116:119]
	v_mfma_f32_16x16x32_bf16 v[104:107], v[164:167], v[188:191], v[104:107]
	v_mfma_f32_16x16x32_bf16 v[100:103], v[172:175], v[188:191], v[100:103]
	v_mfma_f32_16x16x32_bf16 v[88:91], v[164:167], v[204:207], v[88:91]
	v_mfma_f32_16x16x32_bf16 v[84:87], v[172:175], v[204:207], v[84:87]
	v_mfma_f32_16x16x32_bf16 v[72:75], v[164:167], v[212:215], v[72:75]
	v_mfma_f32_16x16x32_bf16 v[68:71], v[172:175], v[212:215], v[68:71]
	v_mfma_f32_16x16x32_bf16 v[120:123], v[168:171], v[184:187], v[120:123]
	v_mfma_f32_16x16x32_bf16 v[116:119], v[176:179], v[184:187], v[116:119]
	v_mfma_f32_16x16x32_bf16 v[104:107], v[168:171], v[192:195], v[104:107]
	v_mfma_f32_16x16x32_bf16 v[100:103], v[176:179], v[192:195], v[100:103]
	v_mfma_f32_16x16x32_bf16 v[88:91], v[168:171], v[208:211], v[88:91]
	v_mfma_f32_16x16x32_bf16 v[84:87], v[176:179], v[208:211], v[84:87]
	v_mfma_f32_16x16x32_bf16 v[72:75], v[168:171], v[230:233], v[72:75]
	v_mfma_f32_16x16x32_bf16 v[68:71], v[176:179], v[230:233], v[68:71]
	s_setprio 0
	s_barrier
	s_add_i32 s52, s66, s27
	s_add_u32 s50, s50, 0x80
	s_addc_u32 s51, s51, 0
	s_mov_b32 m0, s52
	ds_read_b128 v[180:183], v151 offset:49152
	ds_read_b128 v[184:187], v151 offset:50176
	ds_read_b128 v[188:191], v151 offset:51200
	ds_read_b128 v[192:195], v151 offset:52224
	global_load_lds_dwordx4 v2, s[50:51]
	s_add_i32 m0, s52, 0x2000
	s_add_i32 s52, s67, s27
	global_load_lds_dwordx4 v136, s[50:51]
	s_add_u32 s50, s50, 0x80000
	s_addc_u32 s51, s51, 0
	s_mov_b32 m0, s52
	ds_read_b128 v[230:233], v151 offset:56320
	global_load_lds_dwordx4 v2, s[50:51]
	s_add_i32 m0, s52, 0x2000
	ds_read_b128 v[212:215], v151 offset:55296
	global_load_lds_dwordx4 v136, s[50:51]
	s_mov_b32 m0, s58
	ds_read_b128 v[208:211], v151 offset:54272
	global_load_lds_dwordx4 v132, s[86:87]
	s_mov_b32 m0, s59
	ds_read_b128 v[204:207], v151 offset:53248
	global_load_lds_dwordx4 v134, s[86:87]
	s_waitcnt vmcnt(8)
	s_waitcnt lgkmcnt(0)
	s_barrier
	s_setprio 1
	s_waitcnt lgkmcnt(0)
	v_mfma_f32_16x16x32_bf16 v[64:67], v[144:147], v[180:183], v[64:67]
	v_mfma_f32_16x16x32_bf16 v[60:63], v[156:159], v[180:183], v[60:63]
	v_mfma_f32_16x16x32_bf16 v[48:51], v[144:147], v[188:191], v[48:51]
	v_mfma_f32_16x16x32_bf16 v[44:47], v[156:159], v[188:191], v[44:47]
	v_mfma_f32_16x16x32_bf16 v[32:35], v[144:147], v[204:207], v[32:35]
	v_mfma_f32_16x16x32_bf16 v[28:31], v[156:159], v[204:207], v[28:31]
	v_mfma_f32_16x16x32_bf16 v[16:19], v[144:147], v[212:215], v[16:19]
	v_mfma_f32_16x16x32_bf16 v[12:15], v[156:159], v[212:215], v[12:15]
	v_mfma_f32_16x16x32_bf16 v[64:67], v[152:155], v[184:187], v[64:67]
	v_mfma_f32_16x16x32_bf16 v[60:63], v[160:163], v[184:187], v[60:63]
	v_mfma_f32_16x16x32_bf16 v[48:51], v[152:155], v[192:195], v[48:51]
	v_mfma_f32_16x16x32_bf16 v[44:47], v[160:163], v[192:195], v[44:47]
	v_mfma_f32_16x16x32_bf16 v[32:35], v[152:155], v[208:211], v[32:35]
	v_mfma_f32_16x16x32_bf16 v[28:31], v[160:163], v[208:211], v[28:31]
	v_mfma_f32_16x16x32_bf16 v[16:19], v[152:155], v[230:233], v[16:19]
	v_mfma_f32_16x16x32_bf16 v[12:15], v[160:163], v[230:233], v[12:15]
	s_setprio 0
	s_setprio 1
	v_mfma_f32_16x16x32_bf16 v[56:59], v[164:167], v[180:183], v[56:59]
	v_mfma_f32_16x16x32_bf16 v[52:55], v[172:175], v[180:183], v[52:55]
	v_mfma_f32_16x16x32_bf16 v[40:43], v[164:167], v[188:191], v[40:43]
	v_mfma_f32_16x16x32_bf16 v[36:39], v[172:175], v[188:191], v[36:39]
	v_mfma_f32_16x16x32_bf16 v[24:27], v[164:167], v[204:207], v[24:27]
	v_mfma_f32_16x16x32_bf16 v[20:23], v[172:175], v[204:207], v[20:23]
	v_mfma_f32_16x16x32_bf16 v[8:11], v[164:167], v[212:215], v[8:11]
	v_mfma_f32_16x16x32_bf16 v[4:7], v[172:175], v[212:215], v[4:7]
	v_mfma_f32_16x16x32_bf16 v[56:59], v[168:171], v[184:187], v[56:59]
	v_mfma_f32_16x16x32_bf16 v[52:55], v[176:179], v[184:187], v[52:55]
	v_mfma_f32_16x16x32_bf16 v[40:43], v[168:171], v[192:195], v[40:43]
	v_mfma_f32_16x16x32_bf16 v[36:39], v[176:179], v[192:195], v[36:39]
	v_mfma_f32_16x16x32_bf16 v[24:27], v[168:171], v[208:211], v[24:27]
	v_mfma_f32_16x16x32_bf16 v[20:23], v[176:179], v[208:211], v[20:23]
	v_mfma_f32_16x16x32_bf16 v[8:11], v[168:171], v[230:233], v[8:11]
	v_mfma_f32_16x16x32_bf16 v[4:7], v[176:179], v[230:233], v[4:7]
	s_setprio 0
	s_barrier
	s_add_i32 s65, s65, 2
	s_add_u32 s39, s39, 0x100
	s_addc_u32 s43, s43, 0
	s_add_u32 s48, s48, 0x100
	s_addc_u32 s49, s49, 0
	s_cmp_gt_u32 s65, 29
	s_cbranch_scc0 .LBB0_1390
	s_and_b64 vcc, exec, s[34:35]
	s_cbranch_vccz .LBB0_1393
	s_barrier

; #define PG8_STAGE(bufoff, gbase, voff) do { _Pragma("unroll") for (int _i = 0; _i < 2; ++_i) \
;         __builtin_amdgcn_global_load_lds((const unsigned*)((const char*)(gbase) + (voff)[_i]), (LAS unsigned*)(lds + (bufoff) + ldsw + _i * 8192), 16, 0, 0); } while (0)
; #define PG8_LDA(dst, b, h) do { _Pragma("unroll") for (int m = 0; m < 4; ++m) _Pragma("unroll") for (int k = 0; k < 2; ++k) dst[m][k] = *(const LAS bf16x8*)(lds + PG8_SA(b, h) + aoff + m * 2048 + k * 1024); } while (0)
; #define PG8_LDB(dst, b, h) do { _Pragma("unroll") for (int n = 0; n < 2; ++n) _Pragma("unroll") for (int k = 0; k < 2; ++k) dst[n][k] = *(const LAS bf16x8*)(lds + PG8_SB(b, h) + boff + n * 2048 + k * 1024); } while (0)
; #define PG8_MMA(ai, bj, At, Bt) do { __builtin_amdgcn_s_setprio(1); _Pragma("unroll") for (int m = 0; m < 4; ++m) _Pragma("unroll") for (int n = 0; n < 2; ++n) _Pragma("unroll") for (int k = 0; k < 2; ++k) \
;         acc[ai][bj][m][n] = __builtin_amdgcn_mfma_f32_16x16x32_bf16(Bt[n][k], At[m][k], acc[ai][bj][m][n], 0, 0, 0); __builtin_amdgcn_s_setprio(0); } while (0)
; #define PG8_WAIT_V(n) asm volatile("s_waitcnt vmcnt(" #n ")" ::: "memory")
; #define PG8_WAIT_L(n) asm volatile("s_waitcnt lgkmcnt(" #n ")" ::: "memory")
; #define PG8_BAR __builtin_amdgcn_s_barrier()
; template <class Epi, class Sched>
; DI void gemm_phase(LAS unsigned char* lds, const Sched& S, const Epi& E) {
;     ...
;         for (int t = 0; t < nt; t += 2) {
;             const bool last = (t == nt - 2);
;             const char* a1 = cA + (size_t)(t + 1) * kstep;
;             const char* a2 = last ? nA : cA + (size_t)(t + 2) * kstep; const char* b2 = last ? nB : cB + (size_t)(t + 2) * kstep;
;             const char* a3 = a2 + kstep; const char* b3 = b2 + kstep;
;             if constexpr (Epi::HOOK) { if (cur.ks < 0 && (t == 16 || t == 32)) E.hook(acc, cur, t >> 4, wr, wc, fr, fq); }
;             PG8_LDB(B0, 0, 0); PG8_LDB(B1, 0, 1); PG8_SCHED; PG8_LDA(At, 0, 0); PG8_STAGE(PG8_SA(1, 1), a1 + hstepA, voffA);
;             PG8_WAIT_V(8); PG8_WAIT_L(0); PG8_BAR; PG8_MMA(0, 0, At, B0); PG8_MMA(0, 1, At, B1); PG8_BAR; PG8_SCHED;
;             PG8_LDA(At, 0, 1); PG8_STAGE(PG8_SB(0, 0), b2, voffB); PG8_STAGE(PG8_SB(0, 1), b2 + hstepB, voffB); PG8_STAGE(PG8_SA(0, 0), a2, voffA);
;             PG8_WAIT_V(8); PG8_WAIT_L(0); PG8_BAR; PG8_MMA(1, 0, At, B0); PG8_MMA(1, 1, At, B1); PG8_BAR; PG8_SCHED;
.LBB0_1470:
	s_add_i32 s82, s52, 2
	s_add_u32 s53, s42, 0xffe00080
	s_addc_u32 s54, s43, -1
	s_add_i32 s83, 0, 0x10000
	s_cmp_eq_u32 s79, s52
	s_cselect_b32 s55, s56, s54
	s_cselect_b32 s54, s57, s53
	s_cselect_b32 s53, s58, s81
	s_cselect_b32 s52, s59, s80
	s_add_i32 s85, 0, 0x14000
	v_add_u32_e32 v112, s83, v197
	v_add_u32_e32 v160, s85, v197
	ds_read_b128 v[84:87], v112
	ds_read_b128 v[88:91], v112 offset:1024
	ds_read_b128 v[104:107], v112 offset:2048
	ds_read_b128 v[112:115], v112 offset:3072
	ds_read_b128 v[124:127], v160
	ds_read_b128 v[136:139], v160 offset:1024
	ds_read_b128 v[148:151], v160 offset:2048
	ds_read_b128 v[160:163], v160 offset:3072
	s_add_i32 m0, s61, 0xc000
	ds_read_b128 v[164:167], v231
	ds_read_b128 v[168:171], v231 offset:1024
	ds_read_b128 v[172:175], v231 offset:2048
	ds_read_b128 v[176:179], v231 offset:3072
	ds_read_b128 v[180:183], v231 offset:4096
	ds_read_b128 v[184:187], v231 offset:5120
	ds_read_b128 v[188:191], v231 offset:6144
	global_load_lds_dwordx4 v212, s[42:43]
	s_add_i32 m0, s61, 0xe000
	ds_read_b128 v[192:195], v231 offset:7168
	global_load_lds_dwordx4 v210, s[42:43]
	s_waitcnt vmcnt(8)
	s_waitcnt lgkmcnt(0)
	s_barrier
	s_setprio 1
	s_waitcnt lgkmcnt(0)
	v_mfma_f32_16x16x32_bf16 v[156:159], v[84:87], v[164:167], v[156:159]
	v_mfma_f32_16x16x32_bf16 v[152:155], v[104:107], v[164:167], v[152:155]
	v_mfma_f32_16x16x32_bf16 v[132:135], v[84:87], v[172:175], v[132:135]
	v_mfma_f32_16x16x32_bf16 v[128:131], v[104:107], v[172:175], v[128:131]
	v_mfma_f32_16x16x32_bf16 v[108:111], v[84:87], v[180:183], v[108:111]
	v_mfma_f32_16x16x32_bf16 v[100:103], v[104:107], v[180:183], v[100:103]
	v_mfma_f32_16x16x32_bf16 v[80:83], v[84:87], v[188:191], v[80:83]
	v_mfma_f32_16x16x32_bf16 v[76:79], v[104:107], v[188:191], v[76:79]
	v_mfma_f32_16x16x32_bf16 v[156:159], v[88:91], v[168:171], v[156:159]
	v_mfma_f32_16x16x32_bf16 v[152:155], v[112:115], v[168:171], v[152:155]
	v_mfma_f32_16x16x32_bf16 v[132:135], v[88:91], v[176:179], v[132:135]
	v_mfma_f32_16x16x32_bf16 v[128:131], v[112:115], v[176:179], v[128:131]
	v_mfma_f32_16x16x32_bf16 v[108:111], v[88:91], v[184:187], v[108:111]
	v_mfma_f32_16x16x32_bf16 v[100:103], v[112:115], v[184:187], v[100:103]
	v_mfma_f32_16x16x32_bf16 v[80:83], v[88:91], v[192:195], v[80:83]
	v_mfma_f32_16x16x32_bf16 v[76:79], v[112:115], v[192:195], v[76:79]
	s_setprio 0
	s_setprio 1
	v_mfma_f32_16x16x32_bf16 v[144:147], v[124:127], v[164:167], v[144:147]
	v_mfma_f32_16x16x32_bf16 v[140:143], v[148:151], v[164:167], v[140:143]
	v_mfma_f32_16x16x32_bf16 v[120:123], v[124:127], v[172:175], v[120:123]
	v_mfma_f32_16x16x32_bf16 v[116:119], v[148:151], v[172:175], v[116:119]
	v_mfma_f32_16x16x32_bf16 v[96:99], v[124:127], v[180:183], v[96:99]
	v_mfma_f32_16x16x32_bf16 v[92:95], v[148:151], v[180:183], v[92:95]
	v_mfma_f32_16x16x32_bf16 v[72:75], v[124:127], v[188:191], v[72:75]
	v_mfma_f32_16x16x32_bf16 v[68:71], v[148:151], v[188:191], v[68:71]
	v_mfma_f32_16x16x32_bf16 v[144:147], v[136:139], v[168:171], v[144:147]
	v_mfma_f32_16x16x32_bf16 v[140:143], v[160:163], v[168:171], v[140:143]
	v_mfma_f32_16x16x32_bf16 v[120:123], v[136:139], v[176:179], v[120:123]
	v_mfma_f32_16x16x32_bf16 v[116:119], v[160:163], v[176:179], v[116:119]
	v_mfma_f32_16x16x32_bf16 v[96:99], v[136:139], v[184:187], v[96:99]
	v_mfma_f32_16x16x32_bf16 v[92:95], v[160:163], v[184:187], v[92:95]
	v_mfma_f32_16x16x32_bf16 v[72:75], v[136:139], v[192:195], v[72:75]
	v_mfma_f32_16x16x32_bf16 v[68:71], v[160:163], v[192:195], v[68:71]
	s_setprio 0
	s_barrier
	s_add_i32 s83, s83, s60
	s_mov_b32 m0, s83
	ds_read_b128 v[164:167], v231 offset:16384
	ds_read_b128 v[168:171], v231 offset:17408
	ds_read_b128 v[172:175], v231 offset:18432
	ds_read_b128 v[176:179], v231 offset:19456
	global_load_lds_dwordx4 v2, s[52:53]
	s_add_i32 m0, s83, 0x2000
	s_add_u32 s86, s52, 0x200000
	s_addc_u32 s87, s53, 0
	s_add_i32 s83, s85, s60
	global_load_lds_dwordx4 v208, s[52:53]
	s_mov_b32 m0, s83
	ds_read_b128 v[192:195], v231 offset:23552
	global_load_lds_dwordx4 v2, s[86:87]
	s_add_i32 m0, s83, 0x2000
	ds_read_b128 v[188:191], v231 offset:22528
	global_load_lds_dwordx4 v208, s[86:87]
	s_add_u32 s98, s54, 0x80
	s_addc_u32 s99, s55, 0
	s_mov_b32 m0, s61
	ds_read_b128 v[184:187], v231 offset:21504
	global_load_lds_dwordx4 v204, s[54:55]
	s_mov_b32 m0, s62
	ds_read_b128 v[180:183], v231 offset:20480
	global_load_lds_dwordx4 v206, s[54:55]
	s_waitcnt vmcnt(8)
	s_waitcnt lgkmcnt(0)
	s_barrier
	s_setprio 1
	s_waitcnt lgkmcnt(0)
	v_mfma_f32_16x16x32_bf16 v[64:67], v[84:87], v[164:167], v[64:67]
	v_mfma_f32_16x16x32_bf16 v[60:63], v[104:107], v[164:167], v[60:63]
	v_mfma_f32_16x16x32_bf16 v[48:51], v[84:87], v[172:175], v[48:51]
	v_mfma_f32_16x16x32_bf16 v[44:47], v[104:107], v[172:175], v[44:47]
	v_mfma_f32_16x16x32_bf16 v[32:35], v[84:87], v[180:183], v[32:35]
	v_mfma_f32_16x16x32_bf16 v[28:31], v[104:107], v[180:183], v[28:31]
	v_mfma_f32_16x16x32_bf16 v[16:19], v[84:87], v[188:191], v[16:19]
	v_mfma_f32_16x16x32_bf16 v[12:15], v[104:107], v[188:191], v[12:15]
	v_mfma_f32_16x16x32_bf16 v[64:67], v[88:91], v[168:171], v[64:67]
	v_mfma_f32_16x16x32_bf16 v[60:63], v[112:115], v[168:171], v[60:63]
	v_mfma_f32_16x16x32_bf16 v[48:51], v[88:91], v[176:179], v[48:51]
	v_mfma_f32_16x16x32_bf16 v[44:47], v[112:115], v[176:179], v[44:47]
	v_mfma_f32_16x16x32_bf16 v[32:35], v[88:91], v[184:187], v[32:35]
	v_mfma_f32_16x16x32_bf16 v[28:31], v[112:115], v[184:187], v[28:31]
	v_mfma_f32_16x16x32_bf16 v[16:19], v[88:91], v[192:195], v[16:19]
	v_mfma_f32_16x16x32_bf16 v[12:15], v[112:115], v[192:195], v[12:15]
	s_setprio 0
	s_setprio 1
	v_mfma_f32_16x16x32_bf16 v[56:59], v[124:127], v[164:167], v[56:59]
	v_mfma_f32_16x16x32_bf16 v[52:55], v[148:151], v[164:167], v[52:55]
	v_mfma_f32_16x16x32_bf16 v[40:43], v[124:127], v[172:175], v[40:43]
	v_mfma_f32_16x16x32_bf16 v[36:39], v[148:151], v[172:175], v[36:39]
	v_mfma_f32_16x16x32_bf16 v[24:27], v[124:127], v[180:183], v[24:27]
	v_mfma_f32_16x16x32_bf16 v[20:23], v[148:151], v[180:183], v[20:23]
	v_mfma_f32_16x16x32_bf16 v[8:11], v[124:127], v[188:191], v[8:11]
	v_mfma_f32_16x16x32_bf16 v[4:7], v[148:151], v[188:191], v[4:7]
	v_mfma_f32_16x16x32_bf16 v[56:59], v[136:139], v[168:171], v[56:59]
	v_mfma_f32_16x16x32_bf16 v[52:55], v[160:163], v[168:171], v[52:55]
	v_mfma_f32_16x16x32_bf16 v[40:43], v[136:139], v[176:179], v[40:43]
	v_mfma_f32_16x16x32_bf16 v[36:39], v[160:163], v[176:179], v[36:39]
	v_mfma_f32_16x16x32_bf16 v[24:27], v[136:139], v[184:187], v[24:27]
	v_mfma_f32_16x16x32_bf16 v[20:23], v[160:163], v[184:187], v[20:23]
	v_mfma_f32_16x16x32_bf16 v[8:11], v[136:139], v[192:195], v[8:11]
	v_mfma_f32_16x16x32_bf16 v[4:7], v[160:163], v[192:195], v[4:7]
	s_setprio 0
	s_barrier
; #define PG8_STAGE(bufoff, gbase, voff) do { _Pragma("unroll") for (int _i = 0; _i < 2; ++_i) \
;         __builtin_amdgcn_global_load_lds((const unsigned*)((const char*)(gbase) + (voff)[_i]), (LAS unsigned*)(lds + (bufoff) + ldsw + _i * 8192), 16, 0, 0); } while (0)
; #define PG8_LDA(dst, b, h) do { _Pragma("unroll") for (int m = 0; m < 4; ++m) _Pragma("unroll") for (int k = 0; k < 2; ++k) dst[m][k] = *(const LAS bf16x8*)(lds + PG8_SA(b, h) + aoff + m * 2048 + k * 1024); } while (0)
; #define PG8_LDB(dst, b, h) do { _Pragma("unroll") for (int n = 0; n < 2; ++n) _Pragma("unroll") for (int k = 0; k < 2; ++k) dst[n][k] = *(const LAS bf16x8*)(lds + PG8_SB(b, h) + boff + n * 2048 + k * 1024); } while (0)
; #define PG8_MMA(ai, bj, At, Bt) do { __builtin_amdgcn_s_setprio(1); _Pragma("unroll") for (int m = 0; m < 4; ++m) _Pragma("unroll") for (int n = 0; n < 2; ++n) _Pragma("unroll") for (int k = 0; k < 2; ++k) \
;         acc[ai][bj][m][n] = __builtin_amdgcn_mfma_f32_16x16x32_bf16(Bt[n][k], At[m][k], acc[ai][bj][m][n], 0, 0, 0); __builtin_amdgcn_s_setprio(0); } while (0)
; #define PG8_WAIT_V(n) asm volatile("s_waitcnt vmcnt(" #n ")" ::: "memory")
; #define PG8_WAIT_L(n) asm volatile("s_waitcnt lgkmcnt(" #n ")" ::: "memory")
; #define PG8_BAR __builtin_amdgcn_s_barrier()
; #define PG8_SCHED __builtin_amdgcn_sched_barrier(0)
; template <class Epi, class Sched>
; DI void gemm_phase(LAS unsigned char* lds, const Sched& S, const Epi& E) {
;     ...
;             PG8_LDB(B0, 1, 0); PG8_LDB(B1, 1, 1); PG8_SCHED; PG8_LDA(At, 1, 0); PG8_STAGE(PG8_SA(0, 1), a2 + hstepA, voffA);
;             PG8_WAIT_V(8); PG8_WAIT_L(0); PG8_BAR; PG8_MMA(0, 0, At, B0); PG8_MMA(0, 1, At, B1); PG8_BAR; PG8_SCHED;
;             PG8_LDA(At, 1, 1); PG8_STAGE(PG8_SB(1, 0), b3, voffB); PG8_STAGE(PG8_SB(1, 1), b3 + hstepB, voffB); PG8_STAGE(PG8_SA(1, 0), a3, voffA);
;             PG8_WAIT_V(8); PG8_WAIT_L(0); PG8_BAR; PG8_MMA(1, 0, At, B0); PG8_MMA(1, 1, At, B1); PG8_BAR; PG8_SCHED;
;         }
;         if (wr == 0) PG8_BAR;
	s_add_i32 s83, 0, 0x18000
	s_add_i32 s85, 0, 0x1c000
	v_add_u32_e32 v112, s83, v197
	v_add_u32_e32 v160, s85, v197
	ds_read_b128 v[84:87], v112
	ds_read_b128 v[88:91], v112 offset:1024
	ds_read_b128 v[104:107], v112 offset:2048
	ds_read_b128 v[112:115], v112 offset:3072
	ds_read_b128 v[124:127], v160
	ds_read_b128 v[136:139], v160 offset:1024
	ds_read_b128 v[148:151], v160 offset:2048
	ds_read_b128 v[160:163], v160 offset:3072
	s_add_u32 s54, s54, 0x200000
	s_addc_u32 s55, s55, 0
	s_mov_b32 m0, s63
	ds_read_b128 v[164:167], v231 offset:32768
	ds_read_b128 v[168:171], v231 offset:33792
	ds_read_b128 v[172:175], v231 offset:34816
	ds_read_b128 v[176:179], v231 offset:35840
	ds_read_b128 v[180:183], v231 offset:36864
	ds_read_b128 v[184:187], v231 offset:37888
	ds_read_b128 v[188:191], v231 offset:38912
	global_load_lds_dwordx4 v204, s[54:55]
	s_mov_b32 m0, s64
	ds_read_b128 v[192:195], v231 offset:39936
	global_load_lds_dwordx4 v206, s[54:55]
	s_waitcnt vmcnt(8)
	s_waitcnt lgkmcnt(0)
	s_barrier
	s_setprio 1
	s_waitcnt lgkmcnt(0)
	v_mfma_f32_16x16x32_bf16 v[156:159], v[84:87], v[164:167], v[156:159]
	v_mfma_f32_16x16x32_bf16 v[152:155], v[104:107], v[164:167], v[152:155]
	v_mfma_f32_16x16x32_bf16 v[132:135], v[84:87], v[172:175], v[132:135]
	v_mfma_f32_16x16x32_bf16 v[128:131], v[104:107], v[172:175], v[128:131]
	v_mfma_f32_16x16x32_bf16 v[108:111], v[84:87], v[180:183], v[108:111]
	v_mfma_f32_16x16x32_bf16 v[100:103], v[104:107], v[180:183], v[100:103]
	v_mfma_f32_16x16x32_bf16 v[80:83], v[84:87], v[188:191], v[80:83]
	v_mfma_f32_16x16x32_bf16 v[76:79], v[104:107], v[188:191], v[76:79]
	v_mfma_f32_16x16x32_bf16 v[156:159], v[88:91], v[168:171], v[156:159]
	v_mfma_f32_16x16x32_bf16 v[152:155], v[112:115], v[168:171], v[152:155]
	v_mfma_f32_16x16x32_bf16 v[132:135], v[88:91], v[176:179], v[132:135]
	v_mfma_f32_16x16x32_bf16 v[128:131], v[112:115], v[176:179], v[128:131]
	v_mfma_f32_16x16x32_bf16 v[108:111], v[88:91], v[184:187], v[108:111]
	v_mfma_f32_16x16x32_bf16 v[100:103], v[112:115], v[184:187], v[100:103]
	v_mfma_f32_16x16x32_bf16 v[80:83], v[88:91], v[192:195], v[80:83]
	v_mfma_f32_16x16x32_bf16 v[76:79], v[112:115], v[192:195], v[76:79]
	s_setprio 0
	s_setprio 1
	v_mfma_f32_16x16x32_bf16 v[144:147], v[124:127], v[164:167], v[144:147]
	v_mfma_f32_16x16x32_bf16 v[140:143], v[148:151], v[164:167], v[140:143]
	v_mfma_f32_16x16x32_bf16 v[120:123], v[124:127], v[172:175], v[120:123]
	v_mfma_f32_16x16x32_bf16 v[116:119], v[148:151], v[172:175], v[116:119]
	v_mfma_f32_16x16x32_bf16 v[96:99], v[124:127], v[180:183], v[96:99]
	v_mfma_f32_16x16x32_bf16 v[92:95], v[148:151], v[180:183], v[92:95]
	v_mfma_f32_16x16x32_bf16 v[72:75], v[124:127], v[188:191], v[72:75]
	v_mfma_f32_16x16x32_bf16 v[68:71], v[148:151], v[188:191], v[68:71]
	v_mfma_f32_16x16x32_bf16 v[144:147], v[136:139], v[168:171], v[144:147]
	v_mfma_f32_16x16x32_bf16 v[140:143], v[160:163], v[168:171], v[140:143]
	v_mfma_f32_16x16x32_bf16 v[120:123], v[136:139], v[176:179], v[120:123]
	v_mfma_f32_16x16x32_bf16 v[116:119], v[160:163], v[176:179], v[116:119]
	v_mfma_f32_16x16x32_bf16 v[96:99], v[136:139], v[184:187], v[96:99]
	v_mfma_f32_16x16x32_bf16 v[92:95], v[160:163], v[184:187], v[92:95]
	v_mfma_f32_16x16x32_bf16 v[72:75], v[136:139], v[192:195], v[72:75]
	v_mfma_f32_16x16x32_bf16 v[68:71], v[160:163], v[192:195], v[68:71]
	s_setprio 0
	s_barrier
	s_add_i32 s54, s83, s60
	s_add_u32 s52, s52, 0x80
	s_addc_u32 s53, s53, 0
	s_mov_b32 m0, s54
	ds_read_b128 v[164:167], v231 offset:49152
	ds_read_b128 v[168:171], v231 offset:50176
	ds_read_b128 v[172:175], v231 offset:51200
	ds_read_b128 v[176:179], v231 offset:52224
	global_load_lds_dwordx4 v2, s[52:53]
	s_add_i32 m0, s54, 0x2000
	s_add_i32 s54, s85, s60
	global_load_lds_dwordx4 v208, s[52:53]
	s_add_u32 s52, s52, 0x200000
	s_addc_u32 s53, s53, 0
	s_mov_b32 m0, s54
	ds_read_b128 v[192:195], v231 offset:56320
	global_load_lds_dwordx4 v2, s[52:53]
	s_add_i32 m0, s54, 0x2000
	ds_read_b128 v[188:191], v231 offset:55296
	global_load_lds_dwordx4 v208, s[52:53]
	s_mov_b32 m0, s71
	ds_read_b128 v[184:187], v231 offset:54272
	global_load_lds_dwordx4 v204, s[98:99]
	s_mov_b32 m0, s72
	ds_read_b128 v[180:183], v231 offset:53248
	global_load_lds_dwordx4 v206, s[98:99]
	s_waitcnt vmcnt(8)
	s_waitcnt lgkmcnt(0)
	s_barrier
	s_setprio 1
	s_waitcnt lgkmcnt(0)
	v_mfma_f32_16x16x32_bf16 v[64:67], v[84:87], v[164:167], v[64:67]
	v_mfma_f32_16x16x32_bf16 v[60:63], v[104:107], v[164:167], v[60:63]
	v_mfma_f32_16x16x32_bf16 v[48:51], v[84:87], v[172:175], v[48:51]
	v_mfma_f32_16x16x32_bf16 v[44:47], v[104:107], v[172:175], v[44:47]
	v_mfma_f32_16x16x32_bf16 v[32:35], v[84:87], v[180:183], v[32:35]
	v_mfma_f32_16x16x32_bf16 v[28:31], v[104:107], v[180:183], v[28:31]
	v_mfma_f32_16x16x32_bf16 v[16:19], v[84:87], v[188:191], v[16:19]
	v_mfma_f32_16x16x32_bf16 v[12:15], v[104:107], v[188:191], v[12:15]
	v_mfma_f32_16x16x32_bf16 v[64:67], v[88:91], v[168:171], v[64:67]
	v_mfma_f32_16x16x32_bf16 v[60:63], v[112:115], v[168:171], v[60:63]
	v_mfma_f32_16x16x32_bf16 v[48:51], v[88:91], v[176:179], v[48:51]
	v_mfma_f32_16x16x32_bf16 v[44:47], v[112:115], v[176:179], v[44:47]
	v_mfma_f32_16x16x32_bf16 v[32:35], v[88:91], v[184:187], v[32:35]
	v_mfma_f32_16x16x32_bf16 v[28:31], v[112:115], v[184:187], v[28:31]
	v_mfma_f32_16x16x32_bf16 v[16:19], v[88:91], v[192:195], v[16:19]
	v_mfma_f32_16x16x32_bf16 v[12:15], v[112:115], v[192:195], v[12:15]
	s_setprio 0
	s_setprio 1
	v_mfma_f32_16x16x32_bf16 v[56:59], v[124:127], v[164:167], v[56:59]
	v_mfma_f32_16x16x32_bf16 v[52:55], v[148:151], v[164:167], v[52:55]
	v_mfma_f32_16x16x32_bf16 v[40:43], v[124:127], v[172:175], v[40:43]
	v_mfma_f32_16x16x32_bf16 v[36:39], v[148:151], v[172:175], v[36:39]
	v_mfma_f32_16x16x32_bf16 v[24:27], v[124:127], v[180:183], v[24:27]
	v_mfma_f32_16x16x32_bf16 v[20:23], v[148:151], v[180:183], v[20:23]
	v_mfma_f32_16x16x32_bf16 v[8:11], v[124:127], v[188:191], v[8:11]
	v_mfma_f32_16x16x32_bf16 v[4:7], v[148:151], v[188:191], v[4:7]
	v_mfma_f32_16x16x32_bf16 v[56:59], v[136:139], v[168:171], v[56:59]
	v_mfma_f32_16x16x32_bf16 v[52:55], v[160:163], v[168:171], v[52:55]
	v_mfma_f32_16x16x32_bf16 v[40:43], v[136:139], v[176:179], v[40:43]
	v_mfma_f32_16x16x32_bf16 v[36:39], v[160:163], v[176:179], v[36:39]
	v_mfma_f32_16x16x32_bf16 v[24:27], v[136:139], v[184:187], v[24:27]
	v_mfma_f32_16x16x32_bf16 v[20:23], v[160:163], v[184:187], v[20:23]
	v_mfma_f32_16x16x32_bf16 v[8:11], v[136:139], v[192:195], v[8:11]
	v_mfma_f32_16x16x32_bf16 v[4:7], v[160:163], v[192:195], v[4:7]
	s_setprio 0
	s_barrier
	s_add_u32 s80, s80, 0x100
	s_addc_u32 s81, s81, 0
	s_add_u32 s42, s42, 0x100
	s_addc_u32 s43, s43, 0
	s_cmp_ge_i32 s82, s75
	s_mov_b32 s52, s82
	s_cbranch_scc0 .LBB0_1470
	s_and_b64 vcc, exec, s[38:39]
	s_cbranch_vccz .LBB0_1473
	s_barrier
